# v75 + streaming (nt) stores for the in-projection gate tiles and the F0 output Zt, both read only after the attention phase
# speedup vs baseline: 1.0013x; 1.0013x over previous
; __device__ __forceinline__ float sigmoidf_(float x) { return __builtin_amdgcn_rcpf(1.0f + __expf(-x)); }
; #define PG8_PACK8(v0, v1) ((u32x4){cvt_pk_bf16((v0)[0], (v0)[1]), cvt_pk_bf16((v0)[2], (v0)[3]), cvt_pk_bf16((v1)[0], (v1)[1]), cvt_pk_bf16((v1)[2], (v1)[3])})
;     __device__ __forceinline__ void operator()(const f32x4 (&acc)[2][2][4][2], const Unit& u, int wr, int wc, int fr, int fq) const {
;     ...
;             for (int m = 0; m < 4; ++m) { bf16_t* rowp = base + (size_t)(row0 + ai * HALF + m * 16) * ldc + col0;
; #pragma unroll
;                 for (int bj = 0; bj < 2; ++bj) { f32x4 v0 = acc[ai][bj][m][0] + bv[bj][0], v1 = acc[ai][bj][m][1] + bv[bj][1];
;                     if (isg) {
; #pragma unroll
;                         for (int e = 0; e < 4; ++e) { v0[e] = sigmoidf_(v0[e]); v1[e] = sigmoidf_(v1[e]); } }
;                     *(u32x4*)(rowp + bj * HALF) = PG8_PACK8(v0, v1); } }
.LBB0_286:
	s_and_b64 s[36:37], s[36:37], exec
	s_cselect_b32 s25, s17, s15
	s_cselect_b32 s27, s16, s14
	v_mov_b32_e32 v138, s27
	v_mov_b32_e32 v139, s25
	v_lshl_add_u32 v1, s55, 8, v162
	v_lshl_add_u64 v[138:139], v[156:157], 1, v[138:139]
	v_mad_i64_i32 v[140:141], s[36:37], s34, v1, 0
	v_lshl_add_u64 v[140:141], v[140:141], 1, v[138:139]
	v_cvt_pk_bf16_f32 v142, v142, v143
	v_cvt_pk_bf16_f32 v143, v144, v145
	v_cvt_pk_bf16_f32 v144, v160, v161
	v_cvt_pk_bf16_f32 v145, v158, v159
	v_pk_add_f32 v[136:137], v[136:137], v[72:73]
	v_pk_add_f32 v[134:135], v[134:135], v[70:71]
	v_pk_add_f32 v[132:133], v[132:133], v[68:69]
	v_pk_add_f32 v[130:131], v[130:131], v[66:67]
	s_and_b64 vcc, exec, s[8:9]
	s_mov_b64 s[36:37], -1
	s_cbranch_vccnz .Lntg_0
	global_store_dwordx4 v[140:141], v[142:145], off
	s_mov_b64 s[36:37], 0
	s_branch .LBB0_288
.Lntg_0:
	global_store_dwordx4 v[140:141], v[142:145], off nt

; __device__ __forceinline__ float sigmoidf_(float x) { return __builtin_amdgcn_rcpf(1.0f + __expf(-x)); }
; #define PG8_PACK8(v0, v1) ((u32x4){cvt_pk_bf16((v0)[0], (v0)[1]), cvt_pk_bf16((v0)[2], (v0)[3]), cvt_pk_bf16((v1)[0], (v1)[1]), cvt_pk_bf16((v1)[2], (v1)[3])})
;     __device__ __forceinline__ void operator()(const f32x4 (&acc)[2][2][4][2], const Unit& u, int wr, int wc, int fr, int fq) const {
;     ...
;             for (int m = 0; m < 4; ++m) { bf16_t* rowp = base + (size_t)(row0 + ai * HALF + m * 16) * ldc + col0;
; #pragma unroll
;                 for (int bj = 0; bj < 2; ++bj) { f32x4 v0 = acc[ai][bj][m][0] + bv[bj][0], v1 = acc[ai][bj][m][1] + bv[bj][1];
;                     if (isg) {
; #pragma unroll
;                         for (int e = 0; e < 4; ++e) { v0[e] = sigmoidf_(v0[e]); v1[e] = sigmoidf_(v1[e]); } }
;                     *(u32x4*)(rowp + bj * HALF) = PG8_PACK8(v0, v1); } }
.LBB0_290:
	v_cvt_pk_bf16_f32 v134, v134, v135
	v_cvt_pk_bf16_f32 v135, v136, v137
	v_cvt_pk_bf16_f32 v136, v130, v131
	v_cvt_pk_bf16_f32 v137, v132, v133
	v_pk_add_f32 v[128:129], v[128:129], v[80:81]
	v_pk_add_f32 v[126:127], v[126:127], v[78:79]
	v_pk_add_f32 v[124:125], v[124:125], v[76:77]
	v_pk_add_f32 v[130:131], v[122:123], v[74:75]
	s_and_b64 vcc, exec, s[8:9]
	s_mov_b64 s[36:37], -1
	s_cbranch_vccnz .Lntg_1
	global_store_dwordx4 v[140:141], v[134:137], off offset:256
	s_mov_b64 s[36:37], 0
	s_branch .LBB0_292
.Lntg_1:
	global_store_dwordx4 v[140:141], v[134:137], off offset:256 nt

; __device__ __forceinline__ float sigmoidf_(float x) { return __builtin_amdgcn_rcpf(1.0f + __expf(-x)); }
; #define PG8_PACK8(v0, v1) ((u32x4){cvt_pk_bf16((v0)[0], (v0)[1]), cvt_pk_bf16((v0)[2], (v0)[3]), cvt_pk_bf16((v1)[0], (v1)[1]), cvt_pk_bf16((v1)[2], (v1)[3])})
;     __device__ __forceinline__ void operator()(const f32x4 (&acc)[2][2][4][2], const Unit& u, int wr, int wc, int fr, int fq) const {
;     ...
;             for (int m = 0; m < 4; ++m) { bf16_t* rowp = base + (size_t)(row0 + ai * HALF + m * 16) * ldc + col0;
; #pragma unroll
;                 for (int bj = 0; bj < 2; ++bj) { f32x4 v0 = acc[ai][bj][m][0] + bv[bj][0], v1 = acc[ai][bj][m][1] + bv[bj][1];
;                     if (isg) {
; #pragma unroll
;                         for (int e = 0; e < 4; ++e) { v0[e] = sigmoidf_(v0[e]); v1[e] = sigmoidf_(v1[e]); } }
;                     *(u32x4*)(rowp + bj * HALF) = PG8_PACK8(v0, v1); } }
.LBB0_294:
	v_or_b32_e32 v122, 16, v1
	v_mad_i64_i32 v[122:123], s[36:37], s34, v122, 0
	v_lshl_add_u64 v[122:123], v[122:123], 1, v[138:139]
	v_cvt_pk_bf16_f32 v126, v126, v127
	v_cvt_pk_bf16_f32 v127, v128, v129
	v_cvt_pk_bf16_f32 v128, v130, v131
	v_cvt_pk_bf16_f32 v129, v124, v125
	v_pk_add_f32 v[120:121], v[120:121], v[72:73]
	v_pk_add_f32 v[118:119], v[118:119], v[70:71]
	v_pk_add_f32 v[116:117], v[116:117], v[68:69]
	v_pk_add_f32 v[114:115], v[114:115], v[66:67]
	s_and_b64 vcc, exec, s[8:9]
	s_mov_b64 s[36:37], -1
	s_cbranch_vccnz .Lntg_2
	global_store_dwordx4 v[122:123], v[126:129], off
	s_mov_b64 s[36:37], 0
	s_branch .LBB0_296
.Lntg_2:
	global_store_dwordx4 v[122:123], v[126:129], off nt

; __device__ __forceinline__ float sigmoidf_(float x) { return __builtin_amdgcn_rcpf(1.0f + __expf(-x)); }
; #define PG8_PACK8(v0, v1) ((u32x4){cvt_pk_bf16((v0)[0], (v0)[1]), cvt_pk_bf16((v0)[2], (v0)[3]), cvt_pk_bf16((v1)[0], (v1)[1]), cvt_pk_bf16((v1)[2], (v1)[3])})
;     __device__ __forceinline__ void operator()(const f32x4 (&acc)[2][2][4][2], const Unit& u, int wr, int wc, int fr, int fq) const {
;     ...
;             for (int m = 0; m < 4; ++m) { bf16_t* rowp = base + (size_t)(row0 + ai * HALF + m * 16) * ldc + col0;
; #pragma unroll
;                 for (int bj = 0; bj < 2; ++bj) { f32x4 v0 = acc[ai][bj][m][0] + bv[bj][0], v1 = acc[ai][bj][m][1] + bv[bj][1];
;                     if (isg) {
; #pragma unroll
;                         for (int e = 0; e < 4; ++e) { v0[e] = sigmoidf_(v0[e]); v1[e] = sigmoidf_(v1[e]); } }
;                     *(u32x4*)(rowp + bj * HALF) = PG8_PACK8(v0, v1); } }
.LBB0_298:
	v_cvt_pk_bf16_f32 v118, v118, v119
	v_cvt_pk_bf16_f32 v119, v120, v121
	v_cvt_pk_bf16_f32 v120, v114, v115
	v_cvt_pk_bf16_f32 v121, v116, v117
	v_pk_add_f32 v[112:113], v[112:113], v[80:81]
	v_pk_add_f32 v[110:111], v[110:111], v[78:79]
	v_pk_add_f32 v[108:109], v[108:109], v[76:77]
	v_pk_add_f32 v[114:115], v[106:107], v[74:75]
	s_and_b64 vcc, exec, s[8:9]
	s_mov_b64 s[36:37], -1
	s_cbranch_vccnz .Lntg_3
	global_store_dwordx4 v[122:123], v[118:121], off offset:256
	s_mov_b64 s[36:37], 0
	s_branch .LBB0_300
.Lntg_3:
	global_store_dwordx4 v[122:123], v[118:121], off offset:256 nt

; __device__ __forceinline__ float sigmoidf_(float x) { return __builtin_amdgcn_rcpf(1.0f + __expf(-x)); }
; #define PG8_PACK8(v0, v1) ((u32x4){cvt_pk_bf16((v0)[0], (v0)[1]), cvt_pk_bf16((v0)[2], (v0)[3]), cvt_pk_bf16((v1)[0], (v1)[1]), cvt_pk_bf16((v1)[2], (v1)[3])})
;     __device__ __forceinline__ void operator()(const f32x4 (&acc)[2][2][4][2], const Unit& u, int wr, int wc, int fr, int fq) const {
;     ...
;             for (int m = 0; m < 4; ++m) { bf16_t* rowp = base + (size_t)(row0 + ai * HALF + m * 16) * ldc + col0;
; #pragma unroll
;                 for (int bj = 0; bj < 2; ++bj) { f32x4 v0 = acc[ai][bj][m][0] + bv[bj][0], v1 = acc[ai][bj][m][1] + bv[bj][1];
;                     if (isg) {
; #pragma unroll
;                         for (int e = 0; e < 4; ++e) { v0[e] = sigmoidf_(v0[e]); v1[e] = sigmoidf_(v1[e]); } }
;                     *(u32x4*)(rowp + bj * HALF) = PG8_PACK8(v0, v1); } }
.LBB0_302:
	v_or_b32_e32 v106, 32, v1
	v_mad_i64_i32 v[106:107], s[36:37], s34, v106, 0
	v_lshl_add_u64 v[106:107], v[106:107], 1, v[138:139]
	v_cvt_pk_bf16_f32 v110, v110, v111
	v_cvt_pk_bf16_f32 v111, v112, v113
	v_cvt_pk_bf16_f32 v112, v114, v115
	v_cvt_pk_bf16_f32 v113, v108, v109
	v_pk_add_f32 v[104:105], v[104:105], v[72:73]
	v_pk_add_f32 v[102:103], v[102:103], v[70:71]
	v_pk_add_f32 v[100:101], v[100:101], v[68:69]
	v_pk_add_f32 v[98:99], v[98:99], v[66:67]
	s_and_b64 vcc, exec, s[8:9]
	s_mov_b64 s[36:37], -1
	s_cbranch_vccnz .Lntg_4
	global_store_dwordx4 v[106:107], v[110:113], off
	s_mov_b64 s[36:37], 0
	s_branch .LBB0_304
.Lntg_4:
	global_store_dwordx4 v[106:107], v[110:113], off nt

; __device__ __forceinline__ float sigmoidf_(float x) { return __builtin_amdgcn_rcpf(1.0f + __expf(-x)); }
; #define PG8_PACK8(v0, v1) ((u32x4){cvt_pk_bf16((v0)[0], (v0)[1]), cvt_pk_bf16((v0)[2], (v0)[3]), cvt_pk_bf16((v1)[0], (v1)[1]), cvt_pk_bf16((v1)[2], (v1)[3])})
;     __device__ __forceinline__ void operator()(const f32x4 (&acc)[2][2][4][2], const Unit& u, int wr, int wc, int fr, int fq) const {
;     ...
;             for (int m = 0; m < 4; ++m) { bf16_t* rowp = base + (size_t)(row0 + ai * HALF + m * 16) * ldc + col0;
; #pragma unroll
;                 for (int bj = 0; bj < 2; ++bj) { f32x4 v0 = acc[ai][bj][m][0] + bv[bj][0], v1 = acc[ai][bj][m][1] + bv[bj][1];
;                     if (isg) {
; #pragma unroll
;                         for (int e = 0; e < 4; ++e) { v0[e] = sigmoidf_(v0[e]); v1[e] = sigmoidf_(v1[e]); } }
;                     *(u32x4*)(rowp + bj * HALF) = PG8_PACK8(v0, v1); } }
.LBB0_306:
	v_cvt_pk_bf16_f32 v102, v102, v103
	v_cvt_pk_bf16_f32 v103, v104, v105
	v_cvt_pk_bf16_f32 v104, v98, v99
	v_cvt_pk_bf16_f32 v105, v100, v101
	v_pk_add_f32 v[96:97], v[96:97], v[80:81]
	v_pk_add_f32 v[94:95], v[94:95], v[78:79]
	v_pk_add_f32 v[92:93], v[92:93], v[76:77]
	v_pk_add_f32 v[98:99], v[90:91], v[74:75]
	s_and_b64 vcc, exec, s[8:9]
	s_mov_b64 s[36:37], -1
	s_cbranch_vccnz .Lntg_5
	global_store_dwordx4 v[106:107], v[102:105], off offset:256
	s_mov_b64 s[36:37], 0
	s_branch .LBB0_308
.Lntg_5:
	global_store_dwordx4 v[106:107], v[102:105], off offset:256 nt

; __device__ __forceinline__ float sigmoidf_(float x) { return __builtin_amdgcn_rcpf(1.0f + __expf(-x)); }
; #define PG8_PACK8(v0, v1) ((u32x4){cvt_pk_bf16((v0)[0], (v0)[1]), cvt_pk_bf16((v0)[2], (v0)[3]), cvt_pk_bf16((v1)[0], (v1)[1]), cvt_pk_bf16((v1)[2], (v1)[3])})
;     __device__ __forceinline__ void operator()(const f32x4 (&acc)[2][2][4][2], const Unit& u, int wr, int wc, int fr, int fq) const {
;     ...
;             for (int m = 0; m < 4; ++m) { bf16_t* rowp = base + (size_t)(row0 + ai * HALF + m * 16) * ldc + col0;
; #pragma unroll
;                 for (int bj = 0; bj < 2; ++bj) { f32x4 v0 = acc[ai][bj][m][0] + bv[bj][0], v1 = acc[ai][bj][m][1] + bv[bj][1];
;                     if (isg) {
; #pragma unroll
;                         for (int e = 0; e < 4; ++e) { v0[e] = sigmoidf_(v0[e]); v1[e] = sigmoidf_(v1[e]); } }
;                     *(u32x4*)(rowp + bj * HALF) = PG8_PACK8(v0, v1); } }
.LBB0_310:
	v_or_b32_e32 v90, 48, v1
	v_mad_i64_i32 v[90:91], s[36:37], s34, v90, 0
	v_lshl_add_u64 v[90:91], v[90:91], 1, v[138:139]
	v_cvt_pk_bf16_f32 v94, v94, v95
	v_cvt_pk_bf16_f32 v95, v96, v97
	v_cvt_pk_bf16_f32 v96, v98, v99
	v_cvt_pk_bf16_f32 v97, v92, v93
	v_pk_add_f32 v[88:89], v[88:89], v[72:73]
	v_pk_add_f32 v[86:87], v[86:87], v[70:71]
	v_pk_add_f32 v[84:85], v[84:85], v[68:69]
	v_pk_add_f32 v[82:83], v[82:83], v[66:67]
	s_and_b64 vcc, exec, s[8:9]
	s_mov_b64 s[36:37], -1
	s_cbranch_vccnz .Lntg_6
	global_store_dwordx4 v[90:91], v[94:97], off
	s_mov_b64 s[36:37], 0
	s_branch .LBB0_312
.Lntg_6:
	global_store_dwordx4 v[90:91], v[94:97], off nt

; __device__ __forceinline__ float sigmoidf_(float x) { return __builtin_amdgcn_rcpf(1.0f + __expf(-x)); }
; #define PG8_PACK8(v0, v1) ((u32x4){cvt_pk_bf16((v0)[0], (v0)[1]), cvt_pk_bf16((v0)[2], (v0)[3]), cvt_pk_bf16((v1)[0], (v1)[1]), cvt_pk_bf16((v1)[2], (v1)[3])})
;     __device__ __forceinline__ void operator()(const f32x4 (&acc)[2][2][4][2], const Unit& u, int wr, int wc, int fr, int fq) const {
;     ...
;             for (int m = 0; m < 4; ++m) { bf16_t* rowp = base + (size_t)(row0 + ai * HALF + m * 16) * ldc + col0;
; #pragma unroll
;                 for (int bj = 0; bj < 2; ++bj) { f32x4 v0 = acc[ai][bj][m][0] + bv[bj][0], v1 = acc[ai][bj][m][1] + bv[bj][1];
;                     if (isg) {
; #pragma unroll
;                         for (int e = 0; e < 4; ++e) { v0[e] = sigmoidf_(v0[e]); v1[e] = sigmoidf_(v1[e]); } }
;                     *(u32x4*)(rowp + bj * HALF) = PG8_PACK8(v0, v1); } }
.LBB0_314:
	v_cvt_pk_bf16_f32 v86, v86, v87
	v_cvt_pk_bf16_f32 v87, v88, v89
	v_cvt_pk_bf16_f32 v88, v82, v83
	v_cvt_pk_bf16_f32 v89, v84, v85
	v_pk_add_f32 v[64:65], v[64:65], v[80:81]
	v_pk_add_f32 v[62:63], v[62:63], v[78:79]
	v_pk_add_f32 v[60:61], v[60:61], v[76:77]
	v_pk_add_f32 v[82:83], v[58:59], v[74:75]
	s_and_b64 vcc, exec, s[8:9]
	s_mov_b64 s[36:37], -1
	s_cbranch_vccnz .Lntg_7
	global_store_dwordx4 v[90:91], v[86:89], off offset:256
	s_mov_b64 s[36:37], 0
	s_branch .LBB0_316
.Lntg_7:
	global_store_dwordx4 v[90:91], v[86:89], off offset:256 nt

; __device__ __forceinline__ float sigmoidf_(float x) { return __builtin_amdgcn_rcpf(1.0f + __expf(-x)); }
; #define PG8_PACK8(v0, v1) ((u32x4){cvt_pk_bf16((v0)[0], (v0)[1]), cvt_pk_bf16((v0)[2], (v0)[3]), cvt_pk_bf16((v1)[0], (v1)[1]), cvt_pk_bf16((v1)[2], (v1)[3])})
;     __device__ __forceinline__ void operator()(const f32x4 (&acc)[2][2][4][2], const Unit& u, int wr, int wc, int fr, int fq) const {
;     ...
;             for (int m = 0; m < 4; ++m) { bf16_t* rowp = base + (size_t)(row0 + ai * HALF + m * 16) * ldc + col0;
; #pragma unroll
;                 for (int bj = 0; bj < 2; ++bj) { f32x4 v0 = acc[ai][bj][m][0] + bv[bj][0], v1 = acc[ai][bj][m][1] + bv[bj][1];
;                     if (isg) {
; #pragma unroll
;                         for (int e = 0; e < 4; ++e) { v0[e] = sigmoidf_(v0[e]); v1[e] = sigmoidf_(v1[e]); } }
;                     *(u32x4*)(rowp + bj * HALF) = PG8_PACK8(v0, v1); } }
.LBB0_318:
	v_add_u32_e32 v58, 0x80, v1
	v_mad_i64_i32 v[58:59], s[36:37], s34, v58, 0
	v_lshl_add_u64 v[58:59], v[58:59], 1, v[138:139]
	v_cvt_pk_bf16_f32 v62, v62, v63
	v_cvt_pk_bf16_f32 v63, v64, v65
	v_cvt_pk_bf16_f32 v64, v82, v83
	v_cvt_pk_bf16_f32 v65, v60, v61
	v_pk_add_f32 v[56:57], v[56:57], v[72:73]
	v_pk_add_f32 v[54:55], v[54:55], v[70:71]
	v_pk_add_f32 v[52:53], v[52:53], v[68:69]
	v_pk_add_f32 v[50:51], v[50:51], v[66:67]
	s_and_b64 vcc, exec, s[8:9]
	s_mov_b64 s[36:37], -1
	s_cbranch_vccnz .Lntg_8
	global_store_dwordx4 v[58:59], v[62:65], off
	s_mov_b64 s[36:37], 0
	s_branch .LBB0_320
.Lntg_8:
	global_store_dwordx4 v[58:59], v[62:65], off nt

; __device__ __forceinline__ float sigmoidf_(float x) { return __builtin_amdgcn_rcpf(1.0f + __expf(-x)); }
; #define PG8_PACK8(v0, v1) ((u32x4){cvt_pk_bf16((v0)[0], (v0)[1]), cvt_pk_bf16((v0)[2], (v0)[3]), cvt_pk_bf16((v1)[0], (v1)[1]), cvt_pk_bf16((v1)[2], (v1)[3])})
;     __device__ __forceinline__ void operator()(const f32x4 (&acc)[2][2][4][2], const Unit& u, int wr, int wc, int fr, int fq) const {
;     ...
;             for (int m = 0; m < 4; ++m) { bf16_t* rowp = base + (size_t)(row0 + ai * HALF + m * 16) * ldc + col0;
; #pragma unroll
;                 for (int bj = 0; bj < 2; ++bj) { f32x4 v0 = acc[ai][bj][m][0] + bv[bj][0], v1 = acc[ai][bj][m][1] + bv[bj][1];
;                     if (isg) {
; #pragma unroll
;                         for (int e = 0; e < 4; ++e) { v0[e] = sigmoidf_(v0[e]); v1[e] = sigmoidf_(v1[e]); } }
;                     *(u32x4*)(rowp + bj * HALF) = PG8_PACK8(v0, v1); } }
.LBB0_322:
	v_cvt_pk_bf16_f32 v54, v54, v55
	v_cvt_pk_bf16_f32 v55, v56, v57
	v_cvt_pk_bf16_f32 v56, v50, v51
	v_cvt_pk_bf16_f32 v57, v52, v53
	v_pk_add_f32 v[48:49], v[48:49], v[80:81]
	v_pk_add_f32 v[46:47], v[46:47], v[78:79]
	v_pk_add_f32 v[44:45], v[44:45], v[76:77]
	v_pk_add_f32 v[50:51], v[42:43], v[74:75]
	s_and_b64 vcc, exec, s[8:9]
	s_mov_b64 s[36:37], -1
	s_cbranch_vccnz .Lntg_9
	global_store_dwordx4 v[58:59], v[54:57], off offset:256
	s_mov_b64 s[36:37], 0
	s_branch .LBB0_324
.Lntg_9:
	global_store_dwordx4 v[58:59], v[54:57], off offset:256 nt

; __device__ __forceinline__ float sigmoidf_(float x) { return __builtin_amdgcn_rcpf(1.0f + __expf(-x)); }
; #define PG8_PACK8(v0, v1) ((u32x4){cvt_pk_bf16((v0)[0], (v0)[1]), cvt_pk_bf16((v0)[2], (v0)[3]), cvt_pk_bf16((v1)[0], (v1)[1]), cvt_pk_bf16((v1)[2], (v1)[3])})
;     __device__ __forceinline__ void operator()(const f32x4 (&acc)[2][2][4][2], const Unit& u, int wr, int wc, int fr, int fq) const {
;     ...
;             for (int m = 0; m < 4; ++m) { bf16_t* rowp = base + (size_t)(row0 + ai * HALF + m * 16) * ldc + col0;
; #pragma unroll
;                 for (int bj = 0; bj < 2; ++bj) { f32x4 v0 = acc[ai][bj][m][0] + bv[bj][0], v1 = acc[ai][bj][m][1] + bv[bj][1];
;                     if (isg) {
; #pragma unroll
;                         for (int e = 0; e < 4; ++e) { v0[e] = sigmoidf_(v0[e]); v1[e] = sigmoidf_(v1[e]); } }
;                     *(u32x4*)(rowp + bj * HALF) = PG8_PACK8(v0, v1); } }
.LBB0_326:
	v_add_u32_e32 v42, 0x90, v1
	v_mad_i64_i32 v[42:43], s[36:37], s34, v42, 0
	v_lshl_add_u64 v[42:43], v[42:43], 1, v[138:139]
	v_cvt_pk_bf16_f32 v46, v46, v47
	v_cvt_pk_bf16_f32 v47, v48, v49
	v_cvt_pk_bf16_f32 v48, v50, v51
	v_cvt_pk_bf16_f32 v49, v44, v45
	v_pk_add_f32 v[40:41], v[40:41], v[72:73]
	v_pk_add_f32 v[38:39], v[38:39], v[70:71]
	v_pk_add_f32 v[36:37], v[36:37], v[68:69]
	v_pk_add_f32 v[34:35], v[34:35], v[66:67]
	s_and_b64 vcc, exec, s[8:9]
	s_mov_b64 s[36:37], -1
	s_cbranch_vccnz .Lntg_10
	global_store_dwordx4 v[42:43], v[46:49], off
	s_mov_b64 s[36:37], 0
	s_branch .LBB0_328
.Lntg_10:
	global_store_dwordx4 v[42:43], v[46:49], off nt

; __device__ __forceinline__ float sigmoidf_(float x) { return __builtin_amdgcn_rcpf(1.0f + __expf(-x)); }
; #define PG8_PACK8(v0, v1) ((u32x4){cvt_pk_bf16((v0)[0], (v0)[1]), cvt_pk_bf16((v0)[2], (v0)[3]), cvt_pk_bf16((v1)[0], (v1)[1]), cvt_pk_bf16((v1)[2], (v1)[3])})
;     __device__ __forceinline__ void operator()(const f32x4 (&acc)[2][2][4][2], const Unit& u, int wr, int wc, int fr, int fq) const {
;     ...
;             for (int m = 0; m < 4; ++m) { bf16_t* rowp = base + (size_t)(row0 + ai * HALF + m * 16) * ldc + col0;
; #pragma unroll
;                 for (int bj = 0; bj < 2; ++bj) { f32x4 v0 = acc[ai][bj][m][0] + bv[bj][0], v1 = acc[ai][bj][m][1] + bv[bj][1];
;                     if (isg) {
; #pragma unroll
;                         for (int e = 0; e < 4; ++e) { v0[e] = sigmoidf_(v0[e]); v1[e] = sigmoidf_(v1[e]); } }
;                     *(u32x4*)(rowp + bj * HALF) = PG8_PACK8(v0, v1); } }
.LBB0_330:
	v_cvt_pk_bf16_f32 v38, v38, v39
	v_cvt_pk_bf16_f32 v39, v40, v41
	v_cvt_pk_bf16_f32 v40, v34, v35
	v_cvt_pk_bf16_f32 v41, v36, v37
	v_pk_add_f32 v[32:33], v[32:33], v[80:81]
	v_pk_add_f32 v[30:31], v[30:31], v[78:79]
	v_pk_add_f32 v[28:29], v[28:29], v[76:77]
	v_pk_add_f32 v[34:35], v[26:27], v[74:75]
	s_and_b64 vcc, exec, s[8:9]
	s_mov_b64 s[36:37], -1
	s_cbranch_vccnz .Lntg_11
	global_store_dwordx4 v[42:43], v[38:41], off offset:256
	s_mov_b64 s[36:37], 0
	s_branch .LBB0_332
.Lntg_11:
	global_store_dwordx4 v[42:43], v[38:41], off offset:256 nt

; __device__ __forceinline__ float sigmoidf_(float x) { return __builtin_amdgcn_rcpf(1.0f + __expf(-x)); }
; #define PG8_PACK8(v0, v1) ((u32x4){cvt_pk_bf16((v0)[0], (v0)[1]), cvt_pk_bf16((v0)[2], (v0)[3]), cvt_pk_bf16((v1)[0], (v1)[1]), cvt_pk_bf16((v1)[2], (v1)[3])})
;     __device__ __forceinline__ void operator()(const f32x4 (&acc)[2][2][4][2], const Unit& u, int wr, int wc, int fr, int fq) const {
;     ...
;             for (int m = 0; m < 4; ++m) { bf16_t* rowp = base + (size_t)(row0 + ai * HALF + m * 16) * ldc + col0;
; #pragma unroll
;                 for (int bj = 0; bj < 2; ++bj) { f32x4 v0 = acc[ai][bj][m][0] + bv[bj][0], v1 = acc[ai][bj][m][1] + bv[bj][1];
;                     if (isg) {
; #pragma unroll
;                         for (int e = 0; e < 4; ++e) { v0[e] = sigmoidf_(v0[e]); v1[e] = sigmoidf_(v1[e]); } }
;                     *(u32x4*)(rowp + bj * HALF) = PG8_PACK8(v0, v1); } }
.LBB0_334:
	v_add_u32_e32 v26, 0xa0, v1
	v_mad_i64_i32 v[26:27], s[36:37], s34, v26, 0
	v_lshl_add_u64 v[26:27], v[26:27], 1, v[138:139]
	v_cvt_pk_bf16_f32 v30, v30, v31
	v_cvt_pk_bf16_f32 v31, v32, v33
	v_cvt_pk_bf16_f32 v32, v34, v35
	v_cvt_pk_bf16_f32 v33, v28, v29
	v_pk_add_f32 v[24:25], v[24:25], v[72:73]
	v_pk_add_f32 v[22:23], v[22:23], v[70:71]
	v_pk_add_f32 v[20:21], v[20:21], v[68:69]
	v_pk_add_f32 v[18:19], v[18:19], v[66:67]
	s_and_b64 vcc, exec, s[8:9]
	s_mov_b64 s[36:37], -1
	s_cbranch_vccnz .Lntg_12
	global_store_dwordx4 v[26:27], v[30:33], off
	s_mov_b64 s[36:37], 0
	s_branch .LBB0_336
.Lntg_12:
	global_store_dwordx4 v[26:27], v[30:33], off nt

; __device__ __forceinline__ float sigmoidf_(float x) { return __builtin_amdgcn_rcpf(1.0f + __expf(-x)); }
; #define PG8_PACK8(v0, v1) ((u32x4){cvt_pk_bf16((v0)[0], (v0)[1]), cvt_pk_bf16((v0)[2], (v0)[3]), cvt_pk_bf16((v1)[0], (v1)[1]), cvt_pk_bf16((v1)[2], (v1)[3])})
;     __device__ __forceinline__ void operator()(const f32x4 (&acc)[2][2][4][2], const Unit& u, int wr, int wc, int fr, int fq) const {
;     ...
;             for (int m = 0; m < 4; ++m) { bf16_t* rowp = base + (size_t)(row0 + ai * HALF + m * 16) * ldc + col0;
; #pragma unroll
;                 for (int bj = 0; bj < 2; ++bj) { f32x4 v0 = acc[ai][bj][m][0] + bv[bj][0], v1 = acc[ai][bj][m][1] + bv[bj][1];
;                     if (isg) {
; #pragma unroll
;                         for (int e = 0; e < 4; ++e) { v0[e] = sigmoidf_(v0[e]); v1[e] = sigmoidf_(v1[e]); } }
;                     *(u32x4*)(rowp + bj * HALF) = PG8_PACK8(v0, v1); } }
.LBB0_338:
	v_cvt_pk_bf16_f32 v22, v22, v23
	v_cvt_pk_bf16_f32 v23, v24, v25
	v_cvt_pk_bf16_f32 v24, v18, v19
	v_cvt_pk_bf16_f32 v25, v20, v21
	v_pk_add_f32 v[16:17], v[16:17], v[80:81]
	v_pk_add_f32 v[14:15], v[14:15], v[78:79]
	v_pk_add_f32 v[12:13], v[12:13], v[76:77]
	v_pk_add_f32 v[18:19], v[10:11], v[74:75]
	s_and_b64 vcc, exec, s[8:9]
	s_mov_b64 s[36:37], -1
	s_cbranch_vccnz .Lntg_13
	global_store_dwordx4 v[26:27], v[22:25], off offset:256
	s_mov_b64 s[36:37], 0
	s_branch .LBB0_340
.Lntg_13:
	global_store_dwordx4 v[26:27], v[22:25], off offset:256 nt

; #define PG8_PACK8(v0, v1) ((u32x4){cvt_pk_bf16((v0)[0], (v0)[1]), cvt_pk_bf16((v0)[2], (v0)[3]), cvt_pk_bf16((v1)[0], (v1)[1]), cvt_pk_bf16((v1)[2], (v1)[3])})
;     __device__ __forceinline__ void operator()(const f32x4 (&acc)[2][2][4][2], const Unit& u, int wr, int wc, int fr, int fq) const {
;     ...
;                 for (int m = 0; m < 4; ++m) { const int r = u.pm * BM + ai * HALF + wr * 64 + m * 16 + fr;
;                     int part, g, c;
;                     if (r < 520) { part = 0; g = r / 65; c = r - g * 65; } else { const int q = r - 520; part = 1; g = q / 63; c = q - g * 63 + 1; }
;                     const u32x4 v = PG8_PACK8(acc[ai][bj][m][0], acc[ai][bj][m][1]);
;                     const size_t a0 = (((((size_t)(b * 1024 + g * 128 + c)) << lgN2) + s2) * 2 + part) * 128 + wc * 32 + 8 * fq;
;                     *(u32x4*)(Zt + a0) = v;
;                     if (c != 0 && c != 64) { const size_t a1 = (((((size_t)(b * 1024 + g * 128 + 128 - c)) << lgN2) + s2) * 2 + part) * 128 + wc * 32 + 8 * fq;
;                         const unsigned sg = part ? 0x80008000u : 0u; *(u32x4*)(Zt + a1) = (u32x4){v[0] ^ sg, v[1] ^ sg, v[2] ^ sg, v[3] ^ sg}; }
;                     else *(u32x4*)(Zt + a0 + 128) = (u32x4){0u, 0u, 0u, 0u}; } }
.LBB0_368:
	v_lshl_add_u32 v146, s15, 8, v139
	v_add_u32_e32 v154, 0xfffffdf8, v146
	v_cmp_gt_i32_e64 s[8:9], s76, v146
	v_cmp_lt_i32_e32 vcc, s77, v146
	v_mul_hi_u32 v153, v154, s78
	s_and_saveexec_b64 s[10:11], vcc
	s_xor_b64 s[10:11], exec, s[10:11]
	v_sub_u32_e32 v1, v154, v153
	v_lshrrev_b32_e32 v1, 1, v1
	v_add_u32_e32 v1, v1, v153
	v_lshrrev_b32_e32 v1, 5, v1
	v_mul_lo_u32 v148, v1, s79
	v_add3_u32 v148, v146, v148, s45
	s_or_saveexec_b64 s[10:11], s[10:11]
	v_mul_hi_i32 v149, v146, s80
	v_mov_b64_e32 v[150:151], 0x80
	v_lshrrev_b32_e32 v155, 31, v149
	v_ashrrev_i32_e32 v156, 5, v149
	s_xor_b64 exec, exec, s[10:11]
	v_add_u32_e32 v1, v156, v155
	v_mad_u64_u32 v[148:149], s[12:13], v1, s81, v[146:147]
	v_mov_b64_e32 v[150:151], 0
	s_or_b64 exec, exec, s[10:11]
	s_lshl_b32 s37, s14, 1
	s_ashr_i32 s10, s37, s42
	s_lshl_b32 s44, s10, 10
	v_cvt_pk_bf16_f32 v126, v126, v127
	v_cvt_pk_bf16_f32 v127, v128, v129
	v_cvt_pk_bf16_f32 v128, v122, v123
	v_lshl_add_u32 v123, v1, 7, s44
	v_cvt_pk_bf16_f32 v129, v124, v125
	v_add_u32_e32 v124, v123, v148
	v_ashrrev_i32_e32 v125, 31, v124
	s_and_b32 s84, s37, s73
	v_lshlrev_b64 v[124:125], s42, v[124:125]
	v_lshl_add_u64 v[124:125], v[124:125], 0, s[84:85]
	v_lshlrev_b64 v[124:125], 9, v[124:125]
	v_lshl_add_u64 v[124:125], v[140:141], 0, v[124:125]
	v_lshlrev_b32_e32 v226, 1, v150
	v_and_b32_e32 v1, 0xffffffbf, v148
	v_lshl_add_u64 v[124:125], v[124:125], 0, v[226:227]
	v_cmp_ne_u32_e64 s[10:11], 0, v1
	v_cndmask_b32_e64 v1, v242, 0, s[8:9]
	v_lshlrev_b32_e32 v122, 1, v138
	global_store_dwordx4 v[124:125], v[126:129], off nt
	s_and_saveexec_b64 s[8:9], s[10:11]
	s_xor_b64 s[8:9], exec, s[8:9]
	s_cbranch_execz .LBB0_374
	v_sub_u32_e32 v123, v123, v148
	v_add_u32_e32 v124, 0x80, v123
	v_ashrrev_i32_e32 v125, 31, v124
	v_lshlrev_b64 v[124:125], s42, v[124:125]
	v_lshl_add_u64 v[148:149], v[124:125], 0, s[84:85]
	v_xor_b32_e32 v124, v1, v126
	v_xor_b32_e32 v125, v1, v127
	v_xor_b32_e32 v126, v1, v128
	v_xor_b32_e32 v127, v1, v129
	v_lshlrev_b64 v[128:129], 9, v[148:149]
	v_lshl_add_u64 v[128:129], s[28:29], 0, v[128:129]
	v_lshl_add_u64 v[128:129], v[128:129], 0, v[226:227]
	s_lshl_b32 s10, s74, 1
	s_mov_b32 s11, s85
	v_lshl_add_u64 v[128:129], v[128:129], 0, s[10:11]
	v_mov_b32_e32 v123, v227
	v_lshl_add_u64 v[128:129], v[128:129], 0, v[122:123]
	global_store_dwordx4 v[128:129], v[124:127], off nt
.LBB0_374:
	s_andn2_saveexec_b64 s[8:9], s[8:9]
	s_cbranch_execz .LBB0_376
	global_store_dwordx4 v[124:125], v[228:231], off offset:256 nt
.LBB0_376:
	s_or_b64 exec, exec, s[8:9]
	v_or_b32_e32 v124, 16, v146
	v_add_u32_e32 v149, 0xfffffe08, v146
	v_cmp_gt_i32_e64 s[10:11], s76, v124
	v_cmp_lt_i32_e64 s[8:9], s77, v124
	v_mul_hi_u32 v148, v149, s78
	s_and_saveexec_b64 s[12:13], s[8:9]
	s_xor_b64 s[12:13], exec, s[12:13]
	v_sub_u32_e32 v123, v149, v148
	v_lshrrev_b32_e32 v123, 1, v123
	v_add_u32_e32 v123, v123, v148
	v_lshrrev_b32_e32 v123, 5, v123
	v_mul_lo_u32 v125, v123, s79
	v_add3_u32 v126, v146, v125, s48
	s_or_saveexec_b64 s[12:13], s[12:13]
	v_mul_hi_i32 v125, v124, s80
	v_mov_b64_e32 v[128:129], 0x80
	v_lshrrev_b32_e32 v150, 31, v125
	v_ashrrev_i32_e32 v151, 5, v125
	s_xor_b64 exec, exec, s[12:13]
	v_add_u32_e32 v123, v151, v150
	v_mad_u64_u32 v[126:127], s[14:15], v123, s81, v[124:125]
	v_mov_b64_e32 v[128:129], 0
	s_or_b64 exec, exec, s[12:13]
	v_cvt_pk_bf16_f32 v118, v118, v119
	v_cvt_pk_bf16_f32 v119, v120, v121
	v_cvt_pk_bf16_f32 v121, v116, v117
	v_lshl_add_u32 v116, v123, 7, s44
	v_cvt_pk_bf16_f32 v120, v114, v115
	v_add_u32_e32 v114, v116, v126
	v_ashrrev_i32_e32 v115, 31, v114
	v_lshlrev_b64 v[114:115], s42, v[114:115]
	v_lshl_add_u64 v[114:115], v[114:115], 0, s[84:85]
	v_lshlrev_b64 v[114:115], 9, v[114:115]
	v_lshl_add_u64 v[114:115], v[140:141], 0, v[114:115]
	v_lshlrev_b32_e32 v226, 1, v128
	v_and_b32_e32 v117, 0xffffffbf, v126
	v_lshl_add_u64 v[114:115], v[114:115], 0, v[226:227]
	v_cmp_ne_u32_e64 s[12:13], 0, v117
	v_cndmask_b32_e64 v125, v242, 0, s[10:11]
	global_store_dwordx4 v[114:115], v[118:121], off nt
	s_and_saveexec_b64 s[10:11], s[12:13]
	s_xor_b64 s[10:11], exec, s[10:11]
	s_cbranch_execz .LBB0_382
	v_sub_u32_e32 v114, v116, v126
	v_add_u32_e32 v114, 0x80, v114
	v_ashrrev_i32_e32 v115, 31, v114
	v_lshlrev_b64 v[114:115], s42, v[114:115]
	v_lshl_add_u64 v[126:127], v[114:115], 0, s[84:85]
	v_xor_b32_e32 v114, v125, v118
	v_xor_b32_e32 v115, v125, v119
	v_lshlrev_b64 v[118:119], 9, v[126:127]
	v_lshl_add_u64 v[118:119], s[28:29], 0, v[118:119]
	v_lshl_add_u64 v[118:119], v[118:119], 0, v[226:227]
	s_lshl_b32 s12, s74, 1
	s_mov_b32 s13, s85
	v_lshl_add_u64 v[118:119], v[118:119], 0, s[12:13]
	v_mov_b32_e32 v123, v227
	v_xor_b32_e32 v116, v125, v120
	v_xor_b32_e32 v117, v125, v121
	v_lshl_add_u64 v[118:119], v[118:119], 0, v[122:123]
	global_store_dwordx4 v[118:119], v[114:117], off nt
.LBB0_382:
	s_andn2_saveexec_b64 s[10:11], s[10:11]
	s_cbranch_execz .LBB0_384
	global_store_dwordx4 v[114:115], v[228:231], off offset:256 nt
; #define PG8_PACK8(v0, v1) ((u32x4){cvt_pk_bf16((v0)[0], (v0)[1]), cvt_pk_bf16((v0)[2], (v0)[3]), cvt_pk_bf16((v1)[0], (v1)[1]), cvt_pk_bf16((v1)[2], (v1)[3])})
;     __device__ __forceinline__ void operator()(const f32x4 (&acc)[2][2][4][2], const Unit& u, int wr, int wc, int fr, int fq) const {
;     ...
;                 for (int m = 0; m < 4; ++m) { const int r = u.pm * BM + ai * HALF + wr * 64 + m * 16 + fr;
;                     int part, g, c;
;                     if (r < 520) { part = 0; g = r / 65; c = r - g * 65; } else { const int q = r - 520; part = 1; g = q / 63; c = q - g * 63 + 1; }
;                     const u32x4 v = PG8_PACK8(acc[ai][bj][m][0], acc[ai][bj][m][1]);
;                     const size_t a0 = (((((size_t)(b * 1024 + g * 128 + c)) << lgN2) + s2) * 2 + part) * 128 + wc * 32 + 8 * fq;
;                     *(u32x4*)(Zt + a0) = v;
;                     if (c != 0 && c != 64) { const size_t a1 = (((((size_t)(b * 1024 + g * 128 + 128 - c)) << lgN2) + s2) * 2 + part) * 128 + wc * 32 + 8 * fq;
;                         const unsigned sg = part ? 0x80008000u : 0u; *(u32x4*)(Zt + a1) = (u32x4){v[0] ^ sg, v[1] ^ sg, v[2] ^ sg, v[3] ^ sg}; }
;                     else *(u32x4*)(Zt + a0 + 128) = (u32x4){0u, 0u, 0u, 0u}; } }
.LBB0_384:
	s_or_b64 exec, exec, s[10:11]
	v_or_b32_e32 v114, 32, v146
	v_add_u32_e32 v121, 0xfffffe18, v146
	v_cmp_gt_i32_e64 s[12:13], s76, v114
	v_cmp_lt_i32_e64 s[10:11], s77, v114
	v_mul_hi_u32 v120, v121, s78
	s_and_saveexec_b64 s[14:15], s[10:11]
	s_xor_b64 s[14:15], exec, s[14:15]
	v_sub_u32_e32 v115, v121, v120
	v_lshrrev_b32_e32 v115, 1, v115
	v_add_u32_e32 v115, v115, v120
	v_lshrrev_b32_e32 v115, 5, v115
	v_mul_lo_u32 v116, v115, s79
	v_add3_u32 v116, v146, v116, s49
	s_or_saveexec_b64 s[14:15], s[14:15]
	v_mul_hi_i32 v117, v114, s80
	v_mov_b64_e32 v[118:119], 0x80
	v_lshrrev_b32_e32 v126, 31, v117
	v_ashrrev_i32_e32 v127, 5, v117
	s_xor_b64 exec, exec, s[14:15]
	v_add_u32_e32 v115, v127, v126
	v_mad_u64_u32 v[116:117], s[16:17], v115, s81, v[114:115]
	v_mov_b64_e32 v[118:119], 0
	s_or_b64 exec, exec, s[14:15]
	v_cvt_pk_bf16_f32 v110, v110, v111
	v_cvt_pk_bf16_f32 v111, v112, v113
	v_cvt_pk_bf16_f32 v113, v108, v109
	v_lshl_add_u32 v108, v115, 7, s44
	v_cvt_pk_bf16_f32 v112, v106, v107
	v_add_u32_e32 v106, v108, v116
	v_ashrrev_i32_e32 v107, 31, v106
	v_lshlrev_b64 v[106:107], s42, v[106:107]
	v_lshl_add_u64 v[106:107], v[106:107], 0, s[84:85]
	v_lshlrev_b64 v[106:107], 9, v[106:107]
	v_lshl_add_u64 v[106:107], v[140:141], 0, v[106:107]
	v_lshlrev_b32_e32 v226, 1, v118
	v_and_b32_e32 v109, 0xffffffbf, v116
	v_lshl_add_u64 v[106:107], v[106:107], 0, v[226:227]
	v_cmp_ne_u32_e64 s[14:15], 0, v109
	v_cndmask_b32_e64 v115, v242, 0, s[12:13]
	global_store_dwordx4 v[106:107], v[110:113], off nt
	s_and_saveexec_b64 s[12:13], s[14:15]
	s_xor_b64 s[12:13], exec, s[12:13]
	s_cbranch_execz .LBB0_390
	v_sub_u32_e32 v106, v108, v116
	v_add_u32_e32 v106, 0x80, v106
	v_ashrrev_i32_e32 v107, 31, v106
	v_lshlrev_b64 v[106:107], s42, v[106:107]
	v_lshl_add_u64 v[116:117], v[106:107], 0, s[84:85]
	v_xor_b32_e32 v106, v115, v110
	v_xor_b32_e32 v107, v115, v111
	v_lshlrev_b64 v[110:111], 9, v[116:117]
	v_lshl_add_u64 v[110:111], s[28:29], 0, v[110:111]
	v_lshl_add_u64 v[110:111], v[110:111], 0, v[226:227]
	s_lshl_b32 s14, s74, 1
	s_mov_b32 s15, s85
	v_lshl_add_u64 v[110:111], v[110:111], 0, s[14:15]
	v_mov_b32_e32 v123, v227
	v_xor_b32_e32 v108, v115, v112
	v_xor_b32_e32 v109, v115, v113
	v_lshl_add_u64 v[110:111], v[110:111], 0, v[122:123]
	global_store_dwordx4 v[110:111], v[106:109], off nt
.LBB0_390:
	s_andn2_saveexec_b64 s[12:13], s[12:13]
	s_cbranch_execz .LBB0_392
	global_store_dwordx4 v[106:107], v[228:231], off offset:256 nt
.LBB0_392:
	s_or_b64 exec, exec, s[12:13]
	v_or_b32_e32 v106, 48, v146
	v_add_u32_e32 v113, 0xfffffe28, v146
	v_cmp_gt_i32_e64 s[14:15], s76, v106
	v_cmp_lt_i32_e64 s[12:13], s77, v106
	v_mul_hi_u32 v112, v113, s78
	s_and_saveexec_b64 s[16:17], s[12:13]
	s_xor_b64 s[16:17], exec, s[16:17]
	v_sub_u32_e32 v107, v113, v112
	v_lshrrev_b32_e32 v107, 1, v107
	v_add_u32_e32 v107, v107, v112
	v_lshrrev_b32_e32 v107, 5, v107
	v_mul_lo_u32 v108, v107, s79
	v_add3_u32 v108, v146, v108, s59
	s_or_saveexec_b64 s[16:17], s[16:17]
	v_mul_hi_i32 v109, v106, s80
	v_mov_b64_e32 v[110:111], 0x80
	v_lshrrev_b32_e32 v116, 31, v109
	v_ashrrev_i32_e32 v117, 5, v109
	s_xor_b64 exec, exec, s[16:17]
	v_add_u32_e32 v107, v117, v116
	v_mad_u64_u32 v[108:109], s[18:19], v107, s81, v[106:107]
	v_mov_b64_e32 v[110:111], 0
	s_or_b64 exec, exec, s[16:17]
	v_cvt_pk_bf16_f32 v102, v102, v103
	v_cvt_pk_bf16_f32 v103, v104, v105
	v_cvt_pk_bf16_f32 v105, v100, v101
	v_lshl_add_u32 v100, v107, 7, s44
	v_cvt_pk_bf16_f32 v104, v98, v99
	v_add_u32_e32 v98, v100, v108
	v_ashrrev_i32_e32 v99, 31, v98
	v_lshlrev_b64 v[98:99], s42, v[98:99]
	v_lshl_add_u64 v[98:99], v[98:99], 0, s[84:85]
	v_lshlrev_b64 v[98:99], 9, v[98:99]
	v_lshl_add_u64 v[98:99], v[140:141], 0, v[98:99]
	v_lshlrev_b32_e32 v226, 1, v110
	v_and_b32_e32 v101, 0xffffffbf, v108
	v_lshl_add_u64 v[98:99], v[98:99], 0, v[226:227]
	v_cmp_ne_u32_e64 s[16:17], 0, v101
	v_cndmask_b32_e64 v107, v242, 0, s[14:15]
	global_store_dwordx4 v[98:99], v[102:105], off nt
	s_and_saveexec_b64 s[14:15], s[16:17]
	s_xor_b64 s[14:15], exec, s[14:15]
	s_cbranch_execz .LBB0_398
	v_sub_u32_e32 v98, v100, v108
	v_add_u32_e32 v98, 0x80, v98
	v_ashrrev_i32_e32 v99, 31, v98
	v_lshlrev_b64 v[98:99], s42, v[98:99]
	v_lshl_add_u64 v[108:109], v[98:99], 0, s[84:85]
	v_xor_b32_e32 v98, v107, v102
	v_xor_b32_e32 v99, v107, v103
	v_lshlrev_b64 v[102:103], 9, v[108:109]
	v_lshl_add_u64 v[102:103], s[28:29], 0, v[102:103]
	v_lshl_add_u64 v[102:103], v[102:103], 0, v[226:227]
	s_lshl_b32 s16, s74, 1
	s_mov_b32 s17, s85
	v_lshl_add_u64 v[102:103], v[102:103], 0, s[16:17]
	v_mov_b32_e32 v123, v227
	v_xor_b32_e32 v100, v107, v104
	v_xor_b32_e32 v101, v107, v105
	v_lshl_add_u64 v[102:103], v[102:103], 0, v[122:123]
	global_store_dwordx4 v[102:103], v[98:101], off nt
.LBB0_398:
	s_andn2_saveexec_b64 s[14:15], s[14:15]
	s_cbranch_execz .LBB0_400
	global_store_dwordx4 v[98:99], v[228:231], off offset:256 nt
; #define PG8_PACK8(v0, v1) ((u32x4){cvt_pk_bf16((v0)[0], (v0)[1]), cvt_pk_bf16((v0)[2], (v0)[3]), cvt_pk_bf16((v1)[0], (v1)[1]), cvt_pk_bf16((v1)[2], (v1)[3])})
;     __device__ __forceinline__ void operator()(const f32x4 (&acc)[2][2][4][2], const Unit& u, int wr, int wc, int fr, int fq) const {
;     ...
;                 for (int m = 0; m < 4; ++m) { const int r = u.pm * BM + ai * HALF + wr * 64 + m * 16 + fr;
;                     int part, g, c;
;                     if (r < 520) { part = 0; g = r / 65; c = r - g * 65; } else { const int q = r - 520; part = 1; g = q / 63; c = q - g * 63 + 1; }
;                     const u32x4 v = PG8_PACK8(acc[ai][bj][m][0], acc[ai][bj][m][1]);
;                     const size_t a0 = (((((size_t)(b * 1024 + g * 128 + c)) << lgN2) + s2) * 2 + part) * 128 + wc * 32 + 8 * fq;
;                     *(u32x4*)(Zt + a0) = v;
;                     if (c != 0 && c != 64) { const size_t a1 = (((((size_t)(b * 1024 + g * 128 + 128 - c)) << lgN2) + s2) * 2 + part) * 128 + wc * 32 + 8 * fq;
;                         const unsigned sg = part ? 0x80008000u : 0u; *(u32x4*)(Zt + a1) = (u32x4){v[0] ^ sg, v[1] ^ sg, v[2] ^ sg, v[3] ^ sg}; }
;                     else *(u32x4*)(Zt + a0 + 128) = (u32x4){0u, 0u, 0u, 0u}; } }
.LBB0_400:
	s_or_b64 exec, exec, s[14:15]
	v_add_u32_e32 v98, 0x80, v146
	v_add_u32_e32 v105, 0xfffffe78, v146
	v_cmp_gt_i32_e64 s[16:17], s76, v98
	v_cmp_lt_i32_e64 s[14:15], s77, v98
	v_mul_hi_u32 v104, v105, s78
	s_and_saveexec_b64 s[18:19], s[14:15]
	s_xor_b64 s[18:19], exec, s[18:19]
	v_sub_u32_e32 v99, v105, v104
	v_lshrrev_b32_e32 v99, 1, v99
	v_add_u32_e32 v99, v99, v104
	v_lshrrev_b32_e32 v99, 5, v99
	v_mul_lo_u32 v100, v99, s79
	v_add3_u32 v100, v146, v100, s70
	s_or_saveexec_b64 s[18:19], s[18:19]
	v_mul_hi_i32 v101, v98, s80
	v_mov_b64_e32 v[102:103], 0x80
	v_lshrrev_b32_e32 v108, 31, v101
	v_ashrrev_i32_e32 v109, 5, v101
	s_xor_b64 exec, exec, s[18:19]
	v_add_u32_e32 v99, v109, v108
	v_mad_u64_u32 v[100:101], s[20:21], v99, s81, v[98:99]
	v_mov_b64_e32 v[102:103], 0
	s_or_b64 exec, exec, s[18:19]
	v_cvt_pk_bf16_f32 v94, v94, v95
	v_cvt_pk_bf16_f32 v95, v96, v97
	v_cvt_pk_bf16_f32 v97, v92, v93
	v_lshl_add_u32 v92, v99, 7, s44
	v_cvt_pk_bf16_f32 v96, v90, v91
	v_add_u32_e32 v90, v92, v100
	v_ashrrev_i32_e32 v91, 31, v90
	v_lshlrev_b64 v[90:91], s42, v[90:91]
	v_lshl_add_u64 v[90:91], v[90:91], 0, s[84:85]
	v_lshlrev_b64 v[90:91], 9, v[90:91]
	v_lshl_add_u64 v[90:91], v[140:141], 0, v[90:91]
	v_lshlrev_b32_e32 v226, 1, v102
	v_and_b32_e32 v93, 0xffffffbf, v100
	v_lshl_add_u64 v[90:91], v[90:91], 0, v[226:227]
	v_cmp_ne_u32_e64 s[18:19], 0, v93
	v_cndmask_b32_e64 v99, v242, 0, s[16:17]
	global_store_dwordx4 v[90:91], v[94:97], off nt
	s_and_saveexec_b64 s[16:17], s[18:19]
	s_xor_b64 s[16:17], exec, s[16:17]
	s_cbranch_execz .LBB0_406
	v_sub_u32_e32 v90, v92, v100
	v_add_u32_e32 v90, 0x80, v90
	v_ashrrev_i32_e32 v91, 31, v90
	v_lshlrev_b64 v[90:91], s42, v[90:91]
	v_lshl_add_u64 v[100:101], v[90:91], 0, s[84:85]
	v_xor_b32_e32 v90, v99, v94
	v_xor_b32_e32 v91, v99, v95
	v_lshlrev_b64 v[94:95], 9, v[100:101]
	v_lshl_add_u64 v[94:95], s[28:29], 0, v[94:95]
	v_lshl_add_u64 v[94:95], v[94:95], 0, v[226:227]
	s_lshl_b32 s18, s74, 1
	s_mov_b32 s19, s85
	v_lshl_add_u64 v[94:95], v[94:95], 0, s[18:19]
	v_mov_b32_e32 v123, v227
	v_xor_b32_e32 v92, v99, v96
	v_xor_b32_e32 v93, v99, v97
	v_lshl_add_u64 v[94:95], v[94:95], 0, v[122:123]
	global_store_dwordx4 v[94:95], v[90:93], off nt
.LBB0_406:
	s_andn2_saveexec_b64 s[16:17], s[16:17]
	s_cbranch_execz .LBB0_408
	global_store_dwordx4 v[90:91], v[228:231], off offset:256 nt
.LBB0_408:
	s_or_b64 exec, exec, s[16:17]
	v_add_u32_e32 v90, 0x90, v146
	v_add_u32_e32 v97, 0xfffffe88, v146
	v_cmp_gt_i32_e64 s[18:19], s76, v90
	v_cmp_lt_i32_e64 s[16:17], s77, v90
	v_mul_hi_u32 v96, v97, s78
	s_and_saveexec_b64 s[20:21], s[16:17]
	s_xor_b64 s[20:21], exec, s[20:21]
	v_sub_u32_e32 v91, v97, v96
	v_lshrrev_b32_e32 v91, 1, v91
	v_add_u32_e32 v91, v91, v96
	v_lshrrev_b32_e32 v91, 5, v91
	v_mul_lo_u32 v92, v91, s79
	v_add3_u32 v92, v146, v92, s75
	s_or_saveexec_b64 s[20:21], s[20:21]
	v_mul_hi_i32 v93, v90, s80
	v_mov_b64_e32 v[94:95], 0x80
	v_lshrrev_b32_e32 v100, 31, v93
	v_ashrrev_i32_e32 v101, 5, v93
	s_xor_b64 exec, exec, s[20:21]
	v_add_u32_e32 v91, v101, v100
	v_mad_u64_u32 v[92:93], s[22:23], v91, s81, v[90:91]
	v_mov_b64_e32 v[94:95], 0
	s_or_b64 exec, exec, s[20:21]
	v_cvt_pk_bf16_f32 v86, v86, v87
	v_cvt_pk_bf16_f32 v87, v88, v89
	v_cvt_pk_bf16_f32 v89, v84, v85
	v_lshl_add_u32 v84, v91, 7, s44
	v_cvt_pk_bf16_f32 v88, v82, v83
	v_add_u32_e32 v82, v84, v92
	v_ashrrev_i32_e32 v83, 31, v82
	v_lshlrev_b64 v[82:83], s42, v[82:83]
	v_lshl_add_u64 v[82:83], v[82:83], 0, s[84:85]
	v_lshlrev_b64 v[82:83], 9, v[82:83]
	v_lshl_add_u64 v[82:83], v[140:141], 0, v[82:83]
	v_lshlrev_b32_e32 v226, 1, v94
	v_and_b32_e32 v85, 0xffffffbf, v92
	v_lshl_add_u64 v[82:83], v[82:83], 0, v[226:227]
	v_cmp_ne_u32_e64 s[20:21], 0, v85
	v_cndmask_b32_e64 v91, v242, 0, s[18:19]
	global_store_dwordx4 v[82:83], v[86:89], off nt
	s_and_saveexec_b64 s[18:19], s[20:21]
	s_xor_b64 s[18:19], exec, s[18:19]
	s_cbranch_execz .LBB0_414
	v_sub_u32_e32 v82, v84, v92
	v_add_u32_e32 v82, 0x80, v82
	v_ashrrev_i32_e32 v83, 31, v82
	v_lshlrev_b64 v[82:83], s42, v[82:83]
	v_lshl_add_u64 v[92:93], v[82:83], 0, s[84:85]
	v_xor_b32_e32 v82, v91, v86
	v_xor_b32_e32 v83, v91, v87
	v_lshlrev_b64 v[86:87], 9, v[92:93]
	v_lshl_add_u64 v[86:87], s[28:29], 0, v[86:87]
	v_lshl_add_u64 v[86:87], v[86:87], 0, v[226:227]
	s_lshl_b32 s20, s74, 1
	s_mov_b32 s21, s85
	v_lshl_add_u64 v[86:87], v[86:87], 0, s[20:21]
	v_mov_b32_e32 v123, v227
	v_xor_b32_e32 v84, v91, v88
	v_xor_b32_e32 v85, v91, v89
	v_lshl_add_u64 v[86:87], v[86:87], 0, v[122:123]
	global_store_dwordx4 v[86:87], v[82:85], off nt
.LBB0_414:
	s_andn2_saveexec_b64 s[18:19], s[18:19]
	s_cbranch_execz .LBB0_416
	global_store_dwordx4 v[82:83], v[228:231], off offset:256 nt
; #define PG8_PACK8(v0, v1) ((u32x4){cvt_pk_bf16((v0)[0], (v0)[1]), cvt_pk_bf16((v0)[2], (v0)[3]), cvt_pk_bf16((v1)[0], (v1)[1]), cvt_pk_bf16((v1)[2], (v1)[3])})
;     __device__ __forceinline__ void operator()(const f32x4 (&acc)[2][2][4][2], const Unit& u, int wr, int wc, int fr, int fq) const {
;     ...
;                 for (int m = 0; m < 4; ++m) { const int r = u.pm * BM + ai * HALF + wr * 64 + m * 16 + fr;
;                     int part, g, c;
;                     if (r < 520) { part = 0; g = r / 65; c = r - g * 65; } else { const int q = r - 520; part = 1; g = q / 63; c = q - g * 63 + 1; }
;                     const u32x4 v = PG8_PACK8(acc[ai][bj][m][0], acc[ai][bj][m][1]);
;                     const size_t a0 = (((((size_t)(b * 1024 + g * 128 + c)) << lgN2) + s2) * 2 + part) * 128 + wc * 32 + 8 * fq;
;                     *(u32x4*)(Zt + a0) = v;
;                     if (c != 0 && c != 64) { const size_t a1 = (((((size_t)(b * 1024 + g * 128 + 128 - c)) << lgN2) + s2) * 2 + part) * 128 + wc * 32 + 8 * fq;
;                         const unsigned sg = part ? 0x80008000u : 0u; *(u32x4*)(Zt + a1) = (u32x4){v[0] ^ sg, v[1] ^ sg, v[2] ^ sg, v[3] ^ sg}; }
;                     else *(u32x4*)(Zt + a0 + 128) = (u32x4){0u, 0u, 0u, 0u}; } }
.LBB0_416:
	s_or_b64 exec, exec, s[18:19]
	v_add_u32_e32 v82, 0xa0, v146
	v_add_u32_e32 v89, 0xfffffe98, v146
	v_cmp_gt_i32_e64 s[20:21], s76, v82
	v_cmp_lt_i32_e64 s[18:19], s77, v82
	v_mul_hi_u32 v88, v89, s78
	s_and_saveexec_b64 s[22:23], s[18:19]
	s_xor_b64 s[22:23], exec, s[22:23]
	v_sub_u32_e32 v83, v89, v88
	v_lshrrev_b32_e32 v83, 1, v83
	v_add_u32_e32 v83, v83, v88
	v_lshrrev_b32_e32 v83, 5, v83
	v_mul_lo_u32 v84, v83, s79
	s_movk_i32 s24, 0xfe99
	v_add3_u32 v84, v146, v84, s24
	s_or_saveexec_b64 s[22:23], s[22:23]
	v_mul_hi_i32 v85, v82, s80
	v_mov_b64_e32 v[86:87], 0x80
	v_lshrrev_b32_e32 v92, 31, v85
	v_ashrrev_i32_e32 v93, 5, v85
	s_xor_b64 exec, exec, s[22:23]
	v_add_u32_e32 v83, v93, v92
	v_mad_u64_u32 v[84:85], s[24:25], v83, s81, v[82:83]
	v_mov_b64_e32 v[86:87], 0
	s_or_b64 exec, exec, s[22:23]
	v_cvt_pk_bf16_f32 v78, v78, v79
	v_cvt_pk_bf16_f32 v79, v80, v81
	v_cvt_pk_bf16_f32 v81, v76, v77
	v_lshl_add_u32 v76, v83, 7, s44
	v_cvt_pk_bf16_f32 v80, v74, v75
	v_add_u32_e32 v74, v76, v84
	v_ashrrev_i32_e32 v75, 31, v74
	v_lshlrev_b64 v[74:75], s42, v[74:75]
	v_lshl_add_u64 v[74:75], v[74:75], 0, s[84:85]
	v_lshlrev_b64 v[74:75], 9, v[74:75]
	v_lshl_add_u64 v[74:75], v[140:141], 0, v[74:75]
	v_lshlrev_b32_e32 v226, 1, v86
	v_and_b32_e32 v77, 0xffffffbf, v84
	v_lshl_add_u64 v[74:75], v[74:75], 0, v[226:227]
	v_cmp_ne_u32_e64 s[22:23], 0, v77
	v_cndmask_b32_e64 v83, v242, 0, s[20:21]
	global_store_dwordx4 v[74:75], v[78:81], off nt
	s_and_saveexec_b64 s[20:21], s[22:23]
	s_xor_b64 s[20:21], exec, s[20:21]
	s_cbranch_execz .LBB0_422
	v_sub_u32_e32 v74, v76, v84
	v_add_u32_e32 v74, 0x80, v74
	v_ashrrev_i32_e32 v75, 31, v74
	v_lshlrev_b64 v[74:75], s42, v[74:75]
	v_lshl_add_u64 v[84:85], v[74:75], 0, s[84:85]
	v_xor_b32_e32 v74, v83, v78
	v_xor_b32_e32 v75, v83, v79
	v_lshlrev_b64 v[78:79], 9, v[84:85]
	v_lshl_add_u64 v[78:79], s[28:29], 0, v[78:79]
	v_lshl_add_u64 v[78:79], v[78:79], 0, v[226:227]
	s_lshl_b32 s22, s74, 1
	s_mov_b32 s23, s85
	v_lshl_add_u64 v[78:79], v[78:79], 0, s[22:23]
	v_mov_b32_e32 v123, v227
	v_xor_b32_e32 v76, v83, v80
	v_xor_b32_e32 v77, v83, v81
	v_lshl_add_u64 v[78:79], v[78:79], 0, v[122:123]
	global_store_dwordx4 v[78:79], v[74:77], off nt
.LBB0_422:
	s_andn2_saveexec_b64 s[20:21], s[20:21]
	s_cbranch_execz .LBB0_424
	global_store_dwordx4 v[74:75], v[228:231], off offset:256 nt
.LBB0_424:
	s_or_b64 exec, exec, s[20:21]
	v_add_u32_e32 v74, 0xb0, v146
	v_add_u32_e32 v81, 0xfffffea8, v146
	v_cmp_gt_i32_e64 s[22:23], s76, v74
	v_cmp_lt_i32_e64 s[20:21], s77, v74
	v_mul_hi_u32 v80, v81, s78
	s_and_saveexec_b64 s[24:25], s[20:21]
	s_xor_b64 s[24:25], exec, s[24:25]
	v_sub_u32_e32 v75, v81, v80
	v_lshrrev_b32_e32 v75, 1, v75
	v_add_u32_e32 v75, v75, v80
	v_lshrrev_b32_e32 v75, 5, v75
	v_mul_lo_u32 v76, v75, s79
	s_movk_i32 s40, 0xfea9
	v_add3_u32 v76, v146, v76, s40
	s_or_saveexec_b64 s[24:25], s[24:25]
	v_mul_hi_i32 v77, v74, s80
	v_mov_b64_e32 v[78:79], 0x80
	v_lshrrev_b32_e32 v84, 31, v77
	v_ashrrev_i32_e32 v85, 5, v77
	s_xor_b64 exec, exec, s[24:25]
	v_add_u32_e32 v75, v85, v84
	v_mad_u64_u32 v[76:77], s[40:41], v75, s81, v[74:75]
	v_mov_b64_e32 v[78:79], 0
	s_or_b64 exec, exec, s[24:25]
	v_cvt_pk_bf16_f32 v70, v70, v71
	v_cvt_pk_bf16_f32 v71, v72, v73
	v_cvt_pk_bf16_f32 v73, v68, v69
	v_lshl_add_u32 v68, v75, 7, s44
	v_cvt_pk_bf16_f32 v72, v66, v67
	v_add_u32_e32 v66, v68, v76
	v_ashrrev_i32_e32 v67, 31, v66
	v_lshlrev_b64 v[66:67], s42, v[66:67]
	v_lshl_add_u64 v[66:67], v[66:67], 0, s[84:85]
	v_lshlrev_b64 v[66:67], 9, v[66:67]
	v_lshl_add_u64 v[66:67], v[140:141], 0, v[66:67]
	v_lshlrev_b32_e32 v226, 1, v78
	v_and_b32_e32 v69, 0xffffffbf, v76
	v_lshl_add_u64 v[66:67], v[66:67], 0, v[226:227]
	v_cmp_ne_u32_e64 s[24:25], 0, v69
	v_cndmask_b32_e64 v75, v242, 0, s[22:23]
	global_store_dwordx4 v[66:67], v[70:73], off nt
	s_and_saveexec_b64 s[22:23], s[24:25]
	s_xor_b64 s[22:23], exec, s[22:23]
	s_cbranch_execz .LBB0_430
	v_sub_u32_e32 v66, v68, v76
	v_add_u32_e32 v66, 0x80, v66
	v_ashrrev_i32_e32 v67, 31, v66
	v_lshlrev_b64 v[66:67], s42, v[66:67]
	v_lshl_add_u64 v[76:77], v[66:67], 0, s[84:85]
	v_xor_b32_e32 v66, v75, v70
	v_xor_b32_e32 v67, v75, v71
	v_lshlrev_b64 v[70:71], 9, v[76:77]
	v_lshl_add_u64 v[70:71], s[28:29], 0, v[70:71]
	v_lshl_add_u64 v[70:71], v[70:71], 0, v[226:227]
	s_lshl_b32 s84, s74, 1
	v_lshl_add_u64 v[70:71], v[70:71], 0, s[84:85]
	v_mov_b32_e32 v123, v227
	v_xor_b32_e32 v68, v75, v72
	v_xor_b32_e32 v69, v75, v73
	v_lshl_add_u64 v[70:71], v[70:71], 0, v[122:123]
	global_store_dwordx4 v[70:71], v[66:69], off nt
	s_andn2_saveexec_b64 s[22:23], s[22:23]
	s_cbranch_execz .LBB0_432
	s_branch .LBB0_431

;     __device__ __forceinline__ void operator()(const f32x4 (&acc)[2][2][4][2], const Unit& u, int wr, int wc, int fr, int fq) const {
;     ...
;                     if (c != 0 && c != 64) { const size_t a1 = (((((size_t)(b * 1024 + g * 128 + 128 - c)) << lgN2) + s2) * 2 + part) * 128 + wc * 32 + 8 * fq;
;                         const unsigned sg = part ? 0x80008000u : 0u; *(u32x4*)(Zt + a1) = (u32x4){v[0] ^ sg, v[1] ^ sg, v[2] ^ sg, v[3] ^ sg}; }
;                     else *(u32x4*)(Zt + a0 + 128) = (u32x4){0u, 0u, 0u, 0u}; } }
.LBB0_431:
	global_store_dwordx4 v[66:67], v[228:231], off offset:256 nt

; #define PG8_PACK8(v0, v1) ((u32x4){cvt_pk_bf16((v0)[0], (v0)[1]), cvt_pk_bf16((v0)[2], (v0)[3]), cvt_pk_bf16((v1)[0], (v1)[1]), cvt_pk_bf16((v1)[2], (v1)[3])})
;     __device__ __forceinline__ void operator()(const f32x4 (&acc)[2][2][4][2], const Unit& u, int wr, int wc, int fr, int fq) const {
;     ...
;         for (int bj = 0; bj < 2; ++bj) { const int bs = 2 * u.pn + bj, b = bs >> lgN2, s2 = bs & ((1 << lgN2) - 1);
; #pragma unroll
;             for (int ai = 0; ai < 2; ++ai)
; #pragma unroll
;                 for (int m = 0; m < 4; ++m) { const int r = u.pm * BM + ai * HALF + wr * 64 + m * 16 + fr;
;                     int part, g, c;
;                     if (r < 520) { part = 0; g = r / 65; c = r - g * 65; } else { const int q = r - 520; part = 1; g = q / 63; c = q - g * 63 + 1; }
;                     const u32x4 v = PG8_PACK8(acc[ai][bj][m][0], acc[ai][bj][m][1]);
;                     const size_t a0 = (((((size_t)(b * 1024 + g * 128 + c)) << lgN2) + s2) * 2 + part) * 128 + wc * 32 + 8 * fq;
;                     *(u32x4*)(Zt + a0) = v;
;                     if (c != 0 && c != 64) { const size_t a1 = (((((size_t)(b * 1024 + g * 128 + 128 - c)) << lgN2) + s2) * 2 + part) * 128 + wc * 32 + 8 * fq;
;                         const unsigned sg = part ? 0x80008000u : 0u; *(u32x4*)(Zt + a1) = (u32x4){v[0] ^ sg, v[1] ^ sg, v[2] ^ sg, v[3] ^ sg}; }
;                     else *(u32x4*)(Zt + a0 + 128) = (u32x4){0u, 0u, 0u, 0u}; } }
.LBB0_436:
	s_or_b64 exec, exec, s[22:23]
	s_or_b32 s22, s37, 1
	s_ashr_i32 s23, s22, s42
	s_lshl_b32 s24, s23, 10
	v_cvt_pk_bf16_f32 v62, v62, v63
	v_cvt_pk_bf16_f32 v63, v64, v65
	v_cvt_pk_bf16_f32 v65, v60, v61
	v_lshl_add_u32 v60, v70, 7, s24
	v_cvt_pk_bf16_f32 v64, v58, v59
	v_add_u32_e32 v58, v60, v66
	v_ashrrev_i32_e32 v59, 31, v58
	s_and_b32 s84, s22, s73
	v_lshlrev_b64 v[58:59], s42, v[58:59]
	v_lshl_add_u64 v[58:59], v[58:59], 0, s[84:85]
	v_lshlrev_b64 v[58:59], 9, v[58:59]
	v_lshl_add_u64 v[58:59], v[140:141], 0, v[58:59]
	v_lshlrev_b32_e32 v226, 1, v68
	v_and_b32_e32 v61, 0xffffffbf, v66
	v_lshl_add_u64 v[58:59], v[58:59], 0, v[226:227]
	v_cmp_ne_u32_e32 vcc, 0, v61
	global_store_dwordx4 v[58:59], v[62:65], off nt
	s_and_saveexec_b64 s[22:23], vcc
	s_xor_b64 s[22:23], exec, s[22:23]
	s_cbranch_execz .LBB0_438
	v_sub_u32_e32 v58, v60, v66
	v_add_u32_e32 v58, 0x80, v58
	v_ashrrev_i32_e32 v59, 31, v58
	v_lshlrev_b64 v[58:59], s42, v[58:59]
	v_lshl_add_u64 v[66:67], v[58:59], 0, s[84:85]
	v_xor_b32_e32 v58, v1, v62
	v_xor_b32_e32 v59, v1, v63
	v_lshlrev_b64 v[62:63], 9, v[66:67]
	v_lshl_add_u64 v[62:63], s[28:29], 0, v[62:63]
	v_lshl_add_u64 v[62:63], v[62:63], 0, v[226:227]
	s_lshl_b32 s40, s74, 1
	s_mov_b32 s41, s85
	v_lshl_add_u64 v[62:63], v[62:63], 0, s[40:41]
	v_mov_b32_e32 v123, v227
	v_xor_b32_e32 v60, v1, v64
	v_xor_b32_e32 v61, v1, v65
	v_lshl_add_u64 v[62:63], v[62:63], 0, v[122:123]
	global_store_dwordx4 v[62:63], v[58:61], off nt
	s_andn2_saveexec_b64 s[22:23], s[22:23]
	s_cbranch_execz .LBB0_440
	s_branch .LBB0_439

;     __device__ __forceinline__ void operator()(const f32x4 (&acc)[2][2][4][2], const Unit& u, int wr, int wc, int fr, int fq) const {
;     ...
;                     if (c != 0 && c != 64) { const size_t a1 = (((((size_t)(b * 1024 + g * 128 + 128 - c)) << lgN2) + s2) * 2 + part) * 128 + wc * 32 + 8 * fq;
;                         const unsigned sg = part ? 0x80008000u : 0u; *(u32x4*)(Zt + a1) = (u32x4){v[0] ^ sg, v[1] ^ sg, v[2] ^ sg, v[3] ^ sg}; }
;                     else *(u32x4*)(Zt + a0 + 128) = (u32x4){0u, 0u, 0u, 0u}; } }
.LBB0_439:
	global_store_dwordx4 v[58:59], v[228:231], off offset:256 nt

; #define PG8_PACK8(v0, v1) ((u32x4){cvt_pk_bf16((v0)[0], (v0)[1]), cvt_pk_bf16((v0)[2], (v0)[3]), cvt_pk_bf16((v1)[0], (v1)[1]), cvt_pk_bf16((v1)[2], (v1)[3])})
;     __device__ __forceinline__ void operator()(const f32x4 (&acc)[2][2][4][2], const Unit& u, int wr, int wc, int fr, int fq) const {
;     ...
;                     const u32x4 v = PG8_PACK8(acc[ai][bj][m][0], acc[ai][bj][m][1]);
;                     const size_t a0 = (((((size_t)(b * 1024 + g * 128 + c)) << lgN2) + s2) * 2 + part) * 128 + wc * 32 + 8 * fq;
;                     *(u32x4*)(Zt + a0) = v;
;                     if (c != 0 && c != 64) { const size_t a1 = (((((size_t)(b * 1024 + g * 128 + 128 - c)) << lgN2) + s2) * 2 + part) * 128 + wc * 32 + 8 * fq;
;                         const unsigned sg = part ? 0x80008000u : 0u; *(u32x4*)(Zt + a1) = (u32x4){v[0] ^ sg, v[1] ^ sg, v[2] ^ sg, v[3] ^ sg}; }
;                     else *(u32x4*)(Zt + a0 + 128) = (u32x4){0u, 0u, 0u, 0u}; } }
.LBB0_444:
	s_or_b64 exec, exec, s[8:9]
	v_lshl_add_u32 v1, v1, 7, s24
	v_cvt_pk_bf16_f32 v54, v54, v55
	v_cvt_pk_bf16_f32 v55, v56, v57
	v_cvt_pk_bf16_f32 v56, v50, v51
	v_add_u32_e32 v50, v1, v58
	v_ashrrev_i32_e32 v51, 31, v50
	v_lshlrev_b64 v[50:51], s42, v[50:51]
	v_lshl_add_u64 v[50:51], v[50:51], 0, s[84:85]
	v_lshlrev_b64 v[50:51], 9, v[50:51]
	v_cvt_pk_bf16_f32 v57, v52, v53
	v_lshl_add_u64 v[50:51], v[140:141], 0, v[50:51]
	v_lshlrev_b32_e32 v226, 1, v60
	v_and_b32_e32 v52, 0xffffffbf, v58
	v_lshl_add_u64 v[50:51], v[50:51], 0, v[226:227]
	v_cmp_ne_u32_e32 vcc, 0, v52
	global_store_dwordx4 v[50:51], v[54:57], off nt
	s_and_saveexec_b64 s[8:9], vcc
	s_xor_b64 s[8:9], exec, s[8:9]
	s_cbranch_execz .LBB0_446
	v_sub_u32_e32 v1, v1, v58
	v_add_u32_e32 v50, 0x80, v1
	v_ashrrev_i32_e32 v51, 31, v50
	v_lshlrev_b64 v[50:51], s42, v[50:51]
	v_lshl_add_u64 v[58:59], v[50:51], 0, s[84:85]
	v_xor_b32_e32 v50, v125, v54
	v_xor_b32_e32 v51, v125, v55
	v_lshlrev_b64 v[54:55], 9, v[58:59]
	v_lshl_add_u64 v[54:55], s[28:29], 0, v[54:55]
	v_lshl_add_u64 v[54:55], v[54:55], 0, v[226:227]
	s_lshl_b32 s22, s74, 1
	s_mov_b32 s23, s85
	v_lshl_add_u64 v[54:55], v[54:55], 0, s[22:23]
	v_mov_b32_e32 v123, v227
	v_xor_b32_e32 v52, v125, v56
	v_xor_b32_e32 v53, v125, v57
	v_lshl_add_u64 v[54:55], v[54:55], 0, v[122:123]
	global_store_dwordx4 v[54:55], v[50:53], off nt
	s_andn2_saveexec_b64 s[8:9], s[8:9]
	s_cbranch_execz .LBB0_448
	s_branch .LBB0_447

;     __device__ __forceinline__ void operator()(const f32x4 (&acc)[2][2][4][2], const Unit& u, int wr, int wc, int fr, int fq) const {
;     ...
;                     if (c != 0 && c != 64) { const size_t a1 = (((((size_t)(b * 1024 + g * 128 + 128 - c)) << lgN2) + s2) * 2 + part) * 128 + wc * 32 + 8 * fq;
;                         const unsigned sg = part ? 0x80008000u : 0u; *(u32x4*)(Zt + a1) = (u32x4){v[0] ^ sg, v[1] ^ sg, v[2] ^ sg, v[3] ^ sg}; }
;                     else *(u32x4*)(Zt + a0 + 128) = (u32x4){0u, 0u, 0u, 0u}; } }
.LBB0_447:
	global_store_dwordx4 v[50:51], v[228:231], off offset:256 nt

; #define PG8_PACK8(v0, v1) ((u32x4){cvt_pk_bf16((v0)[0], (v0)[1]), cvt_pk_bf16((v0)[2], (v0)[3]), cvt_pk_bf16((v1)[0], (v1)[1]), cvt_pk_bf16((v1)[2], (v1)[3])})
;     __device__ __forceinline__ void operator()(const f32x4 (&acc)[2][2][4][2], const Unit& u, int wr, int wc, int fr, int fq) const {
;     ...
;                     const u32x4 v = PG8_PACK8(acc[ai][bj][m][0], acc[ai][bj][m][1]);
;                     const size_t a0 = (((((size_t)(b * 1024 + g * 128 + c)) << lgN2) + s2) * 2 + part) * 128 + wc * 32 + 8 * fq;
;                     *(u32x4*)(Zt + a0) = v;
;                     if (c != 0 && c != 64) { const size_t a1 = (((((size_t)(b * 1024 + g * 128 + 128 - c)) << lgN2) + s2) * 2 + part) * 128 + wc * 32 + 8 * fq;
;                         const unsigned sg = part ? 0x80008000u : 0u; *(u32x4*)(Zt + a1) = (u32x4){v[0] ^ sg, v[1] ^ sg, v[2] ^ sg, v[3] ^ sg}; }
;                     else *(u32x4*)(Zt + a0 + 128) = (u32x4){0u, 0u, 0u, 0u}; } }
.LBB0_452:
	s_or_b64 exec, exec, s[8:9]
	v_lshl_add_u32 v1, v1, 7, s24
	v_cvt_pk_bf16_f32 v46, v46, v47
	v_cvt_pk_bf16_f32 v47, v48, v49
	v_cvt_pk_bf16_f32 v48, v42, v43
	v_add_u32_e32 v42, v1, v50
	v_ashrrev_i32_e32 v43, 31, v42
	v_lshlrev_b64 v[42:43], s42, v[42:43]
	v_lshl_add_u64 v[42:43], v[42:43], 0, s[84:85]
	v_lshlrev_b64 v[42:43], 9, v[42:43]
	v_cvt_pk_bf16_f32 v49, v44, v45
	v_lshl_add_u64 v[42:43], v[140:141], 0, v[42:43]
	v_lshlrev_b32_e32 v226, 1, v52
	v_and_b32_e32 v44, 0xffffffbf, v50
	v_lshl_add_u64 v[42:43], v[42:43], 0, v[226:227]
	v_cmp_ne_u32_e32 vcc, 0, v44
	global_store_dwordx4 v[42:43], v[46:49], off nt
	s_and_saveexec_b64 s[8:9], vcc
	s_xor_b64 s[8:9], exec, s[8:9]
	s_cbranch_execz .LBB0_454
	v_sub_u32_e32 v1, v1, v50
	v_add_u32_e32 v42, 0x80, v1
	v_ashrrev_i32_e32 v43, 31, v42
	v_lshlrev_b64 v[42:43], s42, v[42:43]
	v_lshl_add_u64 v[50:51], v[42:43], 0, s[84:85]
	v_xor_b32_e32 v42, v115, v46
	v_xor_b32_e32 v43, v115, v47
	v_lshlrev_b64 v[46:47], 9, v[50:51]
	v_lshl_add_u64 v[46:47], s[28:29], 0, v[46:47]
	v_lshl_add_u64 v[46:47], v[46:47], 0, v[226:227]
	s_lshl_b32 s10, s74, 1
	s_mov_b32 s11, s85
	v_lshl_add_u64 v[46:47], v[46:47], 0, s[10:11]
	v_mov_b32_e32 v123, v227
	v_xor_b32_e32 v44, v115, v48
	v_xor_b32_e32 v45, v115, v49
	v_lshl_add_u64 v[46:47], v[46:47], 0, v[122:123]
	global_store_dwordx4 v[46:47], v[42:45], off nt
	s_andn2_saveexec_b64 s[8:9], s[8:9]
	s_cbranch_execz .LBB0_456
	s_branch .LBB0_455

;     __device__ __forceinline__ void operator()(const f32x4 (&acc)[2][2][4][2], const Unit& u, int wr, int wc, int fr, int fq) const {
;     ...
;                     if (c != 0 && c != 64) { const size_t a1 = (((((size_t)(b * 1024 + g * 128 + 128 - c)) << lgN2) + s2) * 2 + part) * 128 + wc * 32 + 8 * fq;
;                         const unsigned sg = part ? 0x80008000u : 0u; *(u32x4*)(Zt + a1) = (u32x4){v[0] ^ sg, v[1] ^ sg, v[2] ^ sg, v[3] ^ sg}; }
;                     else *(u32x4*)(Zt + a0 + 128) = (u32x4){0u, 0u, 0u, 0u}; } }
.LBB0_455:
	global_store_dwordx4 v[42:43], v[228:231], off offset:256 nt

; #define PG8_PACK8(v0, v1) ((u32x4){cvt_pk_bf16((v0)[0], (v0)[1]), cvt_pk_bf16((v0)[2], (v0)[3]), cvt_pk_bf16((v1)[0], (v1)[1]), cvt_pk_bf16((v1)[2], (v1)[3])})
;     __device__ __forceinline__ void operator()(const f32x4 (&acc)[2][2][4][2], const Unit& u, int wr, int wc, int fr, int fq) const {
;     ...
;                     const u32x4 v = PG8_PACK8(acc[ai][bj][m][0], acc[ai][bj][m][1]);
;                     const size_t a0 = (((((size_t)(b * 1024 + g * 128 + c)) << lgN2) + s2) * 2 + part) * 128 + wc * 32 + 8 * fq;
;                     *(u32x4*)(Zt + a0) = v;
;                     if (c != 0 && c != 64) { const size_t a1 = (((((size_t)(b * 1024 + g * 128 + 128 - c)) << lgN2) + s2) * 2 + part) * 128 + wc * 32 + 8 * fq;
;                         const unsigned sg = part ? 0x80008000u : 0u; *(u32x4*)(Zt + a1) = (u32x4){v[0] ^ sg, v[1] ^ sg, v[2] ^ sg, v[3] ^ sg}; }
;                     else *(u32x4*)(Zt + a0 + 128) = (u32x4){0u, 0u, 0u, 0u}; } }
.LBB0_460:
	s_or_b64 exec, exec, s[8:9]
	v_lshl_add_u32 v1, v1, 7, s24
	v_cvt_pk_bf16_f32 v38, v38, v39
	v_cvt_pk_bf16_f32 v39, v40, v41
	v_cvt_pk_bf16_f32 v40, v34, v35
	v_add_u32_e32 v34, v1, v42
	v_ashrrev_i32_e32 v35, 31, v34
	v_lshlrev_b64 v[34:35], s42, v[34:35]
	v_lshl_add_u64 v[34:35], v[34:35], 0, s[84:85]
	v_lshlrev_b64 v[34:35], 9, v[34:35]
	v_cvt_pk_bf16_f32 v41, v36, v37
	v_lshl_add_u64 v[34:35], v[140:141], 0, v[34:35]
	v_lshlrev_b32_e32 v226, 1, v44
	v_and_b32_e32 v36, 0xffffffbf, v42
	v_lshl_add_u64 v[34:35], v[34:35], 0, v[226:227]
	v_cmp_ne_u32_e32 vcc, 0, v36
	global_store_dwordx4 v[34:35], v[38:41], off nt
	s_and_saveexec_b64 s[8:9], vcc
	s_xor_b64 s[8:9], exec, s[8:9]
	s_cbranch_execz .LBB0_462
	v_sub_u32_e32 v1, v1, v42
	v_add_u32_e32 v34, 0x80, v1
	v_ashrrev_i32_e32 v35, 31, v34
	v_lshlrev_b64 v[34:35], s42, v[34:35]
	v_lshl_add_u64 v[42:43], v[34:35], 0, s[84:85]
	v_xor_b32_e32 v34, v107, v38
	v_xor_b32_e32 v35, v107, v39
	v_lshlrev_b64 v[38:39], 9, v[42:43]
	v_lshl_add_u64 v[38:39], s[28:29], 0, v[38:39]
	v_lshl_add_u64 v[38:39], v[38:39], 0, v[226:227]
	s_lshl_b32 s10, s74, 1
	s_mov_b32 s11, s85
	v_lshl_add_u64 v[38:39], v[38:39], 0, s[10:11]
	v_mov_b32_e32 v123, v227
	v_xor_b32_e32 v36, v107, v40
	v_xor_b32_e32 v37, v107, v41
	v_lshl_add_u64 v[38:39], v[38:39], 0, v[122:123]
	global_store_dwordx4 v[38:39], v[34:37], off nt
	s_andn2_saveexec_b64 s[8:9], s[8:9]
	s_cbranch_execz .LBB0_464
	s_branch .LBB0_463

;     __device__ __forceinline__ void operator()(const f32x4 (&acc)[2][2][4][2], const Unit& u, int wr, int wc, int fr, int fq) const {
;     ...
;                     if (c != 0 && c != 64) { const size_t a1 = (((((size_t)(b * 1024 + g * 128 + 128 - c)) << lgN2) + s2) * 2 + part) * 128 + wc * 32 + 8 * fq;
;                         const unsigned sg = part ? 0x80008000u : 0u; *(u32x4*)(Zt + a1) = (u32x4){v[0] ^ sg, v[1] ^ sg, v[2] ^ sg, v[3] ^ sg}; }
;                     else *(u32x4*)(Zt + a0 + 128) = (u32x4){0u, 0u, 0u, 0u}; } }
.LBB0_463:
	global_store_dwordx4 v[34:35], v[228:231], off offset:256 nt

; #define PG8_PACK8(v0, v1) ((u32x4){cvt_pk_bf16((v0)[0], (v0)[1]), cvt_pk_bf16((v0)[2], (v0)[3]), cvt_pk_bf16((v1)[0], (v1)[1]), cvt_pk_bf16((v1)[2], (v1)[3])})
;     __device__ __forceinline__ void operator()(const f32x4 (&acc)[2][2][4][2], const Unit& u, int wr, int wc, int fr, int fq) const {
;     ...
;                     const u32x4 v = PG8_PACK8(acc[ai][bj][m][0], acc[ai][bj][m][1]);
;                     const size_t a0 = (((((size_t)(b * 1024 + g * 128 + c)) << lgN2) + s2) * 2 + part) * 128 + wc * 32 + 8 * fq;
;                     *(u32x4*)(Zt + a0) = v;
;                     if (c != 0 && c != 64) { const size_t a1 = (((((size_t)(b * 1024 + g * 128 + 128 - c)) << lgN2) + s2) * 2 + part) * 128 + wc * 32 + 8 * fq;
;                         const unsigned sg = part ? 0x80008000u : 0u; *(u32x4*)(Zt + a1) = (u32x4){v[0] ^ sg, v[1] ^ sg, v[2] ^ sg, v[3] ^ sg}; }
;                     else *(u32x4*)(Zt + a0 + 128) = (u32x4){0u, 0u, 0u, 0u}; } }
.LBB0_468:
	s_or_b64 exec, exec, s[8:9]
	v_lshl_add_u32 v1, v1, 7, s24
	v_cvt_pk_bf16_f32 v30, v30, v31
	v_cvt_pk_bf16_f32 v31, v32, v33
	v_cvt_pk_bf16_f32 v32, v26, v27
	v_add_u32_e32 v26, v1, v34
	v_ashrrev_i32_e32 v27, 31, v26
	v_lshlrev_b64 v[26:27], s42, v[26:27]
	v_lshl_add_u64 v[26:27], v[26:27], 0, s[84:85]
	v_lshlrev_b64 v[26:27], 9, v[26:27]
	v_cvt_pk_bf16_f32 v33, v28, v29
	v_lshl_add_u64 v[26:27], v[140:141], 0, v[26:27]
	v_lshlrev_b32_e32 v226, 1, v36
	v_and_b32_e32 v28, 0xffffffbf, v34
	v_lshl_add_u64 v[26:27], v[26:27], 0, v[226:227]
	v_cmp_ne_u32_e32 vcc, 0, v28
	global_store_dwordx4 v[26:27], v[30:33], off nt
	s_and_saveexec_b64 s[8:9], vcc
	s_xor_b64 s[8:9], exec, s[8:9]
	s_cbranch_execz .LBB0_470
	v_sub_u32_e32 v1, v1, v34
	v_add_u32_e32 v26, 0x80, v1
	v_ashrrev_i32_e32 v27, 31, v26
	v_lshlrev_b64 v[26:27], s42, v[26:27]
	v_lshl_add_u64 v[34:35], v[26:27], 0, s[84:85]
	v_xor_b32_e32 v26, v99, v30
	v_xor_b32_e32 v27, v99, v31
	v_lshlrev_b64 v[30:31], 9, v[34:35]
	v_lshl_add_u64 v[30:31], s[28:29], 0, v[30:31]
	v_lshl_add_u64 v[30:31], v[30:31], 0, v[226:227]
	s_lshl_b32 s10, s74, 1
	s_mov_b32 s11, s85
	v_lshl_add_u64 v[30:31], v[30:31], 0, s[10:11]
	v_mov_b32_e32 v123, v227
	v_xor_b32_e32 v28, v99, v32
	v_xor_b32_e32 v29, v99, v33
	v_lshl_add_u64 v[30:31], v[30:31], 0, v[122:123]
	global_store_dwordx4 v[30:31], v[26:29], off nt
	s_andn2_saveexec_b64 s[8:9], s[8:9]
	s_cbranch_execz .LBB0_472
	s_branch .LBB0_471

;     __device__ __forceinline__ void operator()(const f32x4 (&acc)[2][2][4][2], const Unit& u, int wr, int wc, int fr, int fq) const {
;     ...
;                     if (c != 0 && c != 64) { const size_t a1 = (((((size_t)(b * 1024 + g * 128 + 128 - c)) << lgN2) + s2) * 2 + part) * 128 + wc * 32 + 8 * fq;
;                         const unsigned sg = part ? 0x80008000u : 0u; *(u32x4*)(Zt + a1) = (u32x4){v[0] ^ sg, v[1] ^ sg, v[2] ^ sg, v[3] ^ sg}; }
;                     else *(u32x4*)(Zt + a0 + 128) = (u32x4){0u, 0u, 0u, 0u}; } }
.LBB0_471:
	global_store_dwordx4 v[26:27], v[228:231], off offset:256 nt

; #define PG8_PACK8(v0, v1) ((u32x4){cvt_pk_bf16((v0)[0], (v0)[1]), cvt_pk_bf16((v0)[2], (v0)[3]), cvt_pk_bf16((v1)[0], (v1)[1]), cvt_pk_bf16((v1)[2], (v1)[3])})
;     __device__ __forceinline__ void operator()(const f32x4 (&acc)[2][2][4][2], const Unit& u, int wr, int wc, int fr, int fq) const {
;     ...
;                     const u32x4 v = PG8_PACK8(acc[ai][bj][m][0], acc[ai][bj][m][1]);
;                     const size_t a0 = (((((size_t)(b * 1024 + g * 128 + c)) << lgN2) + s2) * 2 + part) * 128 + wc * 32 + 8 * fq;
;                     *(u32x4*)(Zt + a0) = v;
;                     if (c != 0 && c != 64) { const size_t a1 = (((((size_t)(b * 1024 + g * 128 + 128 - c)) << lgN2) + s2) * 2 + part) * 128 + wc * 32 + 8 * fq;
;                         const unsigned sg = part ? 0x80008000u : 0u; *(u32x4*)(Zt + a1) = (u32x4){v[0] ^ sg, v[1] ^ sg, v[2] ^ sg, v[3] ^ sg}; }
;                     else *(u32x4*)(Zt + a0 + 128) = (u32x4){0u, 0u, 0u, 0u}; } }
.LBB0_476:
	s_or_b64 exec, exec, s[8:9]
	v_lshl_add_u32 v1, v1, 7, s24
	v_cvt_pk_bf16_f32 v22, v22, v23
	v_cvt_pk_bf16_f32 v23, v24, v25
	v_cvt_pk_bf16_f32 v24, v18, v19
	v_add_u32_e32 v18, v1, v26
	v_ashrrev_i32_e32 v19, 31, v18
	v_lshlrev_b64 v[18:19], s42, v[18:19]
	v_lshl_add_u64 v[18:19], v[18:19], 0, s[84:85]
	v_lshlrev_b64 v[18:19], 9, v[18:19]
	v_cvt_pk_bf16_f32 v25, v20, v21
	v_lshl_add_u64 v[18:19], v[140:141], 0, v[18:19]
	v_lshlrev_b32_e32 v226, 1, v28
	v_and_b32_e32 v20, 0xffffffbf, v26
	v_lshl_add_u64 v[18:19], v[18:19], 0, v[226:227]
	v_cmp_ne_u32_e32 vcc, 0, v20
	global_store_dwordx4 v[18:19], v[22:25], off nt
	s_and_saveexec_b64 s[8:9], vcc
	s_xor_b64 s[8:9], exec, s[8:9]
	s_cbranch_execz .LBB0_478
	v_sub_u32_e32 v1, v1, v26
	v_add_u32_e32 v18, 0x80, v1
	v_ashrrev_i32_e32 v19, 31, v18
	v_lshlrev_b64 v[18:19], s42, v[18:19]
	v_lshl_add_u64 v[26:27], v[18:19], 0, s[84:85]
	v_xor_b32_e32 v18, v91, v22
	v_xor_b32_e32 v19, v91, v23
	v_lshlrev_b64 v[22:23], 9, v[26:27]
	v_lshl_add_u64 v[22:23], s[28:29], 0, v[22:23]
	v_lshl_add_u64 v[22:23], v[22:23], 0, v[226:227]
	s_lshl_b32 s10, s74, 1
	s_mov_b32 s11, s85
	v_lshl_add_u64 v[22:23], v[22:23], 0, s[10:11]
	v_mov_b32_e32 v123, v227
	v_xor_b32_e32 v20, v91, v24
	v_xor_b32_e32 v21, v91, v25
	v_lshl_add_u64 v[22:23], v[22:23], 0, v[122:123]
	global_store_dwordx4 v[22:23], v[18:21], off nt
	s_andn2_saveexec_b64 s[8:9], s[8:9]
	s_cbranch_execz .LBB0_480
	s_branch .LBB0_479

;     __device__ __forceinline__ void operator()(const f32x4 (&acc)[2][2][4][2], const Unit& u, int wr, int wc, int fr, int fq) const {
;     ...
;                     if (c != 0 && c != 64) { const size_t a1 = (((((size_t)(b * 1024 + g * 128 + 128 - c)) << lgN2) + s2) * 2 + part) * 128 + wc * 32 + 8 * fq;
;                         const unsigned sg = part ? 0x80008000u : 0u; *(u32x4*)(Zt + a1) = (u32x4){v[0] ^ sg, v[1] ^ sg, v[2] ^ sg, v[3] ^ sg}; }
;                     else *(u32x4*)(Zt + a0 + 128) = (u32x4){0u, 0u, 0u, 0u}; } }
.LBB0_479:
	global_store_dwordx4 v[18:19], v[228:231], off offset:256 nt

; #define PG8_PACK8(v0, v1) ((u32x4){cvt_pk_bf16((v0)[0], (v0)[1]), cvt_pk_bf16((v0)[2], (v0)[3]), cvt_pk_bf16((v1)[0], (v1)[1]), cvt_pk_bf16((v1)[2], (v1)[3])})
;     __device__ __forceinline__ void operator()(const f32x4 (&acc)[2][2][4][2], const Unit& u, int wr, int wc, int fr, int fq) const {
;     ...
;                     const u32x4 v = PG8_PACK8(acc[ai][bj][m][0], acc[ai][bj][m][1]);
;                     const size_t a0 = (((((size_t)(b * 1024 + g * 128 + c)) << lgN2) + s2) * 2 + part) * 128 + wc * 32 + 8 * fq;
;                     *(u32x4*)(Zt + a0) = v;
;                     if (c != 0 && c != 64) { const size_t a1 = (((((size_t)(b * 1024 + g * 128 + 128 - c)) << lgN2) + s2) * 2 + part) * 128 + wc * 32 + 8 * fq;
;                         const unsigned sg = part ? 0x80008000u : 0u; *(u32x4*)(Zt + a1) = (u32x4){v[0] ^ sg, v[1] ^ sg, v[2] ^ sg, v[3] ^ sg}; }
;                     else *(u32x4*)(Zt + a0 + 128) = (u32x4){0u, 0u, 0u, 0u}; } }
.LBB0_484:
	s_or_b64 exec, exec, s[8:9]
	v_lshl_add_u32 v1, v1, 7, s24
	v_cvt_pk_bf16_f32 v14, v14, v15
	v_cvt_pk_bf16_f32 v15, v16, v17
	v_cvt_pk_bf16_f32 v16, v10, v11
	v_add_u32_e32 v10, v1, v18
	v_ashrrev_i32_e32 v11, 31, v10
	v_lshlrev_b64 v[10:11], s42, v[10:11]
	v_lshl_add_u64 v[10:11], v[10:11], 0, s[84:85]
	v_lshlrev_b64 v[10:11], 9, v[10:11]
	v_cvt_pk_bf16_f32 v17, v12, v13
	v_lshl_add_u64 v[10:11], v[140:141], 0, v[10:11]
	v_lshlrev_b32_e32 v226, 1, v20
	v_and_b32_e32 v12, 0xffffffbf, v18
	v_lshl_add_u64 v[10:11], v[10:11], 0, v[226:227]
	v_cmp_ne_u32_e32 vcc, 0, v12
	global_store_dwordx4 v[10:11], v[14:17], off nt
	s_and_saveexec_b64 s[8:9], vcc
	s_xor_b64 s[8:9], exec, s[8:9]
	s_cbranch_execz .LBB0_486
	v_sub_u32_e32 v1, v1, v18
	v_add_u32_e32 v10, 0x80, v1
	v_ashrrev_i32_e32 v11, 31, v10
	v_lshlrev_b64 v[10:11], s42, v[10:11]
	v_lshl_add_u64 v[18:19], v[10:11], 0, s[84:85]
	v_xor_b32_e32 v10, v83, v14
	v_xor_b32_e32 v11, v83, v15
	v_lshlrev_b64 v[14:15], 9, v[18:19]
	v_lshl_add_u64 v[14:15], s[28:29], 0, v[14:15]
	v_lshl_add_u64 v[14:15], v[14:15], 0, v[226:227]
	s_lshl_b32 s10, s74, 1
	s_mov_b32 s11, s85
	v_lshl_add_u64 v[14:15], v[14:15], 0, s[10:11]
	v_mov_b32_e32 v123, v227
	v_xor_b32_e32 v12, v83, v16
	v_xor_b32_e32 v13, v83, v17
	v_lshl_add_u64 v[14:15], v[14:15], 0, v[122:123]
	global_store_dwordx4 v[14:15], v[10:13], off nt
	s_andn2_saveexec_b64 s[8:9], s[8:9]
	s_cbranch_execz .LBB0_488
	s_branch .LBB0_487

;     __device__ __forceinline__ void operator()(const f32x4 (&acc)[2][2][4][2], const Unit& u, int wr, int wc, int fr, int fq) const {
;     ...
;                     if (c != 0 && c != 64) { const size_t a1 = (((((size_t)(b * 1024 + g * 128 + 128 - c)) << lgN2) + s2) * 2 + part) * 128 + wc * 32 + 8 * fq;
;                         const unsigned sg = part ? 0x80008000u : 0u; *(u32x4*)(Zt + a1) = (u32x4){v[0] ^ sg, v[1] ^ sg, v[2] ^ sg, v[3] ^ sg}; }
;                     else *(u32x4*)(Zt + a0 + 128) = (u32x4){0u, 0u, 0u, 0u}; } }
.LBB0_487:
	global_store_dwordx4 v[10:11], v[228:231], off offset:256 nt

; #define PG8_PACK8(v0, v1) ((u32x4){cvt_pk_bf16((v0)[0], (v0)[1]), cvt_pk_bf16((v0)[2], (v0)[3]), cvt_pk_bf16((v1)[0], (v1)[1]), cvt_pk_bf16((v1)[2], (v1)[3])})
;     __device__ __forceinline__ void operator()(const f32x4 (&acc)[2][2][4][2], const Unit& u, int wr, int wc, int fr, int fq) const {
;     ...
;                     const u32x4 v = PG8_PACK8(acc[ai][bj][m][0], acc[ai][bj][m][1]);
;                     const size_t a0 = (((((size_t)(b * 1024 + g * 128 + c)) << lgN2) + s2) * 2 + part) * 128 + wc * 32 + 8 * fq;
;                     *(u32x4*)(Zt + a0) = v;
;                     if (c != 0 && c != 64) { const size_t a1 = (((((size_t)(b * 1024 + g * 128 + 128 - c)) << lgN2) + s2) * 2 + part) * 128 + wc * 32 + 8 * fq;
;                         const unsigned sg = part ? 0x80008000u : 0u; *(u32x4*)(Zt + a1) = (u32x4){v[0] ^ sg, v[1] ^ sg, v[2] ^ sg, v[3] ^ sg}; }
;                     else *(u32x4*)(Zt + a0 + 128) = (u32x4){0u, 0u, 0u, 0u}; } }
.LBB0_492:
	s_or_b64 exec, exec, s[8:9]
	v_lshl_add_u32 v1, v1, 7, s24
	v_cvt_pk_bf16_f32 v6, v6, v7
	v_cvt_pk_bf16_f32 v7, v8, v9
	v_cvt_pk_bf16_f32 v8, v2, v3
	v_add_u32_e32 v2, v1, v10
	v_ashrrev_i32_e32 v3, 31, v2
	v_lshlrev_b64 v[2:3], s42, v[2:3]
	v_lshl_add_u64 v[2:3], v[2:3], 0, s[84:85]
	v_lshlrev_b64 v[2:3], 9, v[2:3]
	v_cvt_pk_bf16_f32 v9, v4, v5
	v_lshl_add_u64 v[2:3], v[140:141], 0, v[2:3]
	v_lshlrev_b32_e32 v226, 1, v12
	v_and_b32_e32 v4, 0xffffffbf, v10
	v_lshl_add_u64 v[2:3], v[2:3], 0, v[226:227]
	v_cmp_ne_u32_e32 vcc, 0, v4
	global_store_dwordx4 v[2:3], v[6:9], off nt
	s_and_saveexec_b64 s[8:9], vcc
	s_xor_b64 s[8:9], exec, s[8:9]
	s_cbranch_execz .LBB0_495
	v_sub_u32_e32 v1, v1, v10
	v_add_u32_e32 v2, 0x80, v1
	v_ashrrev_i32_e32 v3, 31, v2
	v_lshlrev_b64 v[2:3], s42, v[2:3]
	v_lshl_add_u64 v[10:11], v[2:3], 0, s[84:85]
	v_xor_b32_e32 v2, v75, v6
	v_xor_b32_e32 v3, v75, v7
	v_lshlrev_b64 v[6:7], 9, v[10:11]
	v_lshl_add_u64 v[6:7], s[28:29], 0, v[6:7]
	v_lshl_add_u64 v[6:7], v[6:7], 0, v[226:227]
	s_lshl_b32 s84, s74, 1
	v_lshl_add_u64 v[6:7], v[6:7], 0, s[84:85]
	v_mov_b32_e32 v123, v227
	v_xor_b32_e32 v4, v75, v8
	v_xor_b32_e32 v5, v75, v9
	v_lshl_add_u64 v[6:7], v[6:7], 0, v[122:123]
	global_store_dwordx4 v[6:7], v[2:5], off nt
	s_andn2_saveexec_b64 s[8:9], s[8:9]
	s_cbranch_execnz .LBB0_496

;     __device__ __forceinline__ void operator()(const f32x4 (&acc)[2][2][4][2], const Unit& u, int wr, int wc, int fr, int fq) const {
;     ...
;                     if (c != 0 && c != 64) { const size_t a1 = (((((size_t)(b * 1024 + g * 128 + 128 - c)) << lgN2) + s2) * 2 + part) * 128 + wc * 32 + 8 * fq;
;                         const unsigned sg = part ? 0x80008000u : 0u; *(u32x4*)(Zt + a1) = (u32x4){v[0] ^ sg, v[1] ^ sg, v[2] ^ sg, v[3] ^ sg}; }
;                     else *(u32x4*)(Zt + a0 + 128) = (u32x4){0u, 0u, 0u, 0u}; } }
; template <class Prob, class Epi, class Sched>
; __device__ __forceinline__ void gemm_phase(PG8_LAS unsigned char* lds, const Prob g, const Sched& S, const Epi& E) {
;     ...
;         if (!has_next) break;
.LBB0_496:
	global_store_dwordx4 v[2:3], v[228:231], off offset:256 nt
	s_or_b64 exec, exec, s[8:9]
	s_and_b64 vcc, exec, s[6:7]
	s_mov_b64 s[6:7], -1
	s_cbranch_vccnz .LBB0_355
